# sgemm_sample: four staging register sets (three K slabs in flight) and the epilogue's residual / norm loads hoisted above the K loop
# speedup vs baseline: 1.0310x; 1.0055x over previous
; template <int MODE>
; __device__ __forceinline__ void sgemm_sample(LAS unsigned char* lds, const bf16_t* A, const bf16_t* Bt, int K, const float* resid, float* out, bf16_t* xb, float* ssq_out, const float* ssq_in) {
;     ...
;     for (int uu = u; uu < 2048; uu += gridDim.x * 8) {
;         const int rt = uu >> 6, ct = uu & 63; const int row = NTOKP + rt * 16 + fr, col0 = ct * 16 + fq * 4;
;         const bf16_t* ap = A + (size_t)row * K + fq * 8; const bf16_t* bp = Bt + (size_t)(ct * 16 + fr) * K + fq * 8;
;         f32x4 acc = {0.f, 0.f, 0.f, 0.f};
; #pragma unroll 8
;         for (int ks = 0; ks < K / 32; ++ks) {
;             const bf16x8 a = *(const bf16x8*)(ap + ks * 32); const bf16x8 b = *(const bf16x8*)(bp + ks * 32);
;             acc = __builtin_amdgcn_mfma_f32_16x16x32_bf16(b, a, acc, 0, 0, 0);
;         }
;         if (MODE == 0) {
;             const f32x4 x = *(const f32x4*)(resid + (size_t)(row - NTOKP) * D + col0) + acc;
.LBB0_894:
	s_and_b32 s6, s15, 63
	v_lshl_or_b32 v4, s6, 15, v21
	s_ashr_i32 s6, s3, 2
	s_and_b32 s6, s6, -16
	s_add_i32 s6, s6, 0x8000
	v_or_b32_e32 v12, s6, v17
	v_ashrrev_i32_e32 v13, 31, v12
	v_lshlrev_b64 v[8:9], 11, v[12:13]
	v_lshl_add_u64 v[10:11], v[6:7], 0, v[4:5]
	v_lshl_add_u64 v[14:15], v[6:7], 0, v[8:9]
	s_mov_b64 s[16:17], 0
	v_mov_b32_e32 v0, 0
	v_mov_b32_e32 v1, v5
	v_mov_b32_e32 v2, v5
	v_mov_b32_e32 v3, v5
	s_cmpk_lg_i32 s34, 0x100
	s_cbranch_scc1 .LBB0_895
	s_waitcnt vmcnt(0)
	s_and_b32 s18, s3, 63
	v_lshl_or_b32 v24, s18, 4, v18
	v_lshlrev_b64 v[14:15], 12, v[12:13]
	v_lshl_add_u64 v[10:11], s[40:41], 0, v[14:15]
	v_lshlrev_b32_e32 v4, 2, v24
	v_lshl_add_u64 v[10:11], v[10:11], 0, v[4:5]
	v_add_co_u32_e32 v10, vcc, 0xf8000000, v10
	v_lshl_add_u64 v[14:15], s[90:91], 0, v[14:15]
	s_nop 0
	v_addc_co_u32_e32 v11, vcc, -1, v11, vcc
	global_load_dwordx4 v[10:13], v[10:11], off
	s_lshr_b32 s100, s2, 3
	s_lshl_b32 s100, s100, 4
	s_add_i32 s100, s100, 0x8000
	s_mul_i32 s100, s100, 0x800
	s_add_u32 s96, s92, s100
	s_addc_u32 s97, s93, 0
	s_add_u32 s96, s96, 0x15780000
	s_addc_u32 s97, s97, 0
	s_and_b32 s100, s2, 7
	s_lshl_b32 s100, s100, 7
	s_mul_i32 s100, s100, 0x800
	s_add_u32 s98, s92, s100
	s_addc_u32 s99, s93, 0
	s_add_u32 s98, s98, 0x840000
	s_addc_u32 s99, s99, 0
	v_lshrrev_b32_e32 v192, 4, v200
	v_and_b32_e32 v193, 15, v200
	v_and_b32_e32 v194, 15, v192
	v_xor_b32_e32 v193, v193, v194
	v_lshlrev_b32_e32 v193, 4, v193
	s_mov_b32 s100, 0x800
	v_mad_u32_u24 v144, v192, s100, v193
	v_add_u32_e32 v145, 0x10000, v144
	v_add_u32_e32 v146, 0x20000, v144
	v_add_u32_e32 v147, 0x30000, v144
	v_mad_u32_u24 v148, v194, s100, v193
	v_lshlrev_b32_e32 v149, 4, v200
	v_add_u32_e32 v149, 1024, v149
	v_and_b32_e32 v150, 0xff, v200
	v_lshlrev_b32_e32 v150, 4, v150
	v_add_u32_e32 v150, 33792, v150
	v_and_b32_e32 v192, 15, v200
	v_bfe_u32 v193, v200, 4, 2
	v_and_b32_e32 v194, 3, v192
	v_xor_b32_e32 v193, v193, v194
	v_lshlrev_b32_e32 v193, 4, v193
	v_lshrrev_b32_e32 v194, 2, v192
	v_lshl_add_u32 v193, v194, 6, v193
	v_lshl_add_u32 v193, v192, 8, v193
	v_add_u32_e32 v151, 33792, v193
	v_lshrrev_b32_e32 v194, 6, v200
	v_lshlrev_b32_e32 v194, 12, v194
	v_add_u32_e32 v155, v193, v194
	v_add_u32_e32 v155, 1024, v155
	v_xor_b32_e32 v152, 0x40, v151
	v_xor_b32_e32 v156, 0x40, v155
	v_xor_b32_e32 v153, 0x80, v151
	v_xor_b32_e32 v157, 0x80, v155
	v_xor_b32_e32 v154, 0xc0, v151
	v_xor_b32_e32 v158, 0xc0, v155
	global_load_dwordx4 v[64:67], v144, s[98:99]
	global_load_dwordx4 v[68:71], v145, s[98:99]
	global_load_dwordx4 v[72:75], v146, s[98:99]
	global_load_dwordx4 v[76:79], v147, s[98:99]
	global_load_dwordx4 v[80:83], v148, s[96:97]
	s_add_u32 s98, s98, 0x100
	s_addc_u32 s99, s99, 0
	s_add_u32 s96, s96, 0x100
	s_addc_u32 s97, s97, 0
	global_load_dwordx4 v[84:87], v144, s[98:99]
	global_load_dwordx4 v[88:91], v145, s[98:99]
	global_load_dwordx4 v[92:95], v146, s[98:99]
	global_load_dwordx4 v[96:99], v147, s[98:99]
	global_load_dwordx4 v[100:103], v148, s[96:97]
	s_add_u32 s98, s98, 0x100
	s_addc_u32 s99, s99, 0
	s_add_u32 s96, s96, 0x100
	s_addc_u32 s97, s97, 0
	global_load_dwordx4 v[104:107], v144, s[98:99]
	global_load_dwordx4 v[108:111], v145, s[98:99]
	global_load_dwordx4 v[112:115], v146, s[98:99]
	global_load_dwordx4 v[116:119], v147, s[98:99]
	global_load_dwordx4 v[120:123], v148, s[96:97]
	s_add_u32 s98, s98, 0x100
	s_addc_u32 s99, s99, 0
	s_add_u32 s96, s96, 0x100
	s_addc_u32 s97, s97, 0
	global_load_dwordx4 v[124:127], v144, s[98:99]
	global_load_dwordx4 v[128:131], v145, s[98:99]
	global_load_dwordx4 v[132:135], v146, s[98:99]
	global_load_dwordx4 v[136:139], v147, s[98:99]
	global_load_dwordx4 v[140:143], v148, s[96:97]
	s_add_u32 s98, s98, 0x100
	s_addc_u32 s99, s99, 0
	s_add_u32 s96, s96, 0x100
	s_addc_u32 s97, s97, 0
	s_waitcnt vmcnt(19)
	ds_write_b128 v149, v[64:67]
	s_waitcnt vmcnt(18)
	ds_write_b128 v149, v[68:71] offset:8192
	s_waitcnt vmcnt(17)
	ds_write_b128 v149, v[72:75] offset:16384
	s_waitcnt vmcnt(16)
	ds_write_b128 v149, v[76:79] offset:24576
	s_waitcnt vmcnt(15)
	ds_write_b128 v150, v[80:83]
	s_waitcnt lgkmcnt(0)
	s_barrier
	s_waitcnt vmcnt(14)
	ds_write_b128 v149, v[84:87] offset:36864
	s_waitcnt vmcnt(13)
	ds_write_b128 v149, v[88:91] offset:45056
	s_waitcnt vmcnt(12)
	ds_write_b128 v149, v[92:95] offset:53248
	s_waitcnt vmcnt(11)
	ds_write_b128 v149, v[96:99] offset:61440
	s_waitcnt vmcnt(10)
	ds_write_b128 v150, v[100:103] offset:36864
	global_load_dwordx4 v[64:67], v144, s[98:99]
	global_load_dwordx4 v[68:71], v145, s[98:99]
	global_load_dwordx4 v[72:75], v146, s[98:99]
	global_load_dwordx4 v[76:79], v147, s[98:99]
	global_load_dwordx4 v[80:83], v148, s[96:97]
	s_add_u32 s98, s98, 0x100
	s_addc_u32 s99, s99, 0
	s_add_u32 s96, s96, 0x100
	s_addc_u32 s97, s97, 0
	ds_read_b128 v[160:163], v155
	ds_read_b128 v[164:167], v151
	ds_read_b128 v[168:171], v156
	ds_read_b128 v[172:175], v152
	ds_read_b128 v[176:179], v157
	ds_read_b128 v[180:183], v153
	ds_read_b128 v[184:187], v158
	ds_read_b128 v[188:191], v154
	s_waitcnt lgkmcnt(6)
	v_mfma_f32_16x16x32_bf16 v[0:3], v[160:163], v[164:167], v[0:3]
	s_waitcnt lgkmcnt(4)
	v_mfma_f32_16x16x32_bf16 v[0:3], v[168:171], v[172:175], v[0:3]
	s_waitcnt lgkmcnt(2)
	v_mfma_f32_16x16x32_bf16 v[0:3], v[176:179], v[180:183], v[0:3]
	s_waitcnt lgkmcnt(0)
	v_mfma_f32_16x16x32_bf16 v[0:3], v[184:187], v[188:191], v[0:3]
	s_waitcnt lgkmcnt(0)
	s_barrier
; template <int MODE>
; __device__ __forceinline__ void sgemm_sample(LAS unsigned char* lds, const bf16_t* A, const bf16_t* Bt, int K, const float* resid, float* out, bf16_t* xb, float* ssq_out, const float* ssq_in) {
;     ...
; #pragma unroll 8
;         for (int ks = 0; ks < K / 32; ++ks) {
;             const bf16x8 a = *(const bf16x8*)(ap + ks * 32); const bf16x8 b = *(const bf16x8*)(bp + ks * 32);
;             acc = __builtin_amdgcn_mfma_f32_16x16x32_bf16(b, a, acc, 0, 0, 0);
;         }
	s_waitcnt vmcnt(14)
	ds_write_b128 v149, v[104:107]
	s_waitcnt vmcnt(13)
	ds_write_b128 v149, v[108:111] offset:8192
	s_waitcnt vmcnt(12)
	ds_write_b128 v149, v[112:115] offset:16384
	s_waitcnt vmcnt(11)
	ds_write_b128 v149, v[116:119] offset:24576
	s_waitcnt vmcnt(10)
	ds_write_b128 v150, v[120:123]
	global_load_dwordx4 v[84:87], v144, s[98:99]
	global_load_dwordx4 v[88:91], v145, s[98:99]
	global_load_dwordx4 v[92:95], v146, s[98:99]
	global_load_dwordx4 v[96:99], v147, s[98:99]
	global_load_dwordx4 v[100:103], v148, s[96:97]
	s_add_u32 s98, s98, 0x100
	s_addc_u32 s99, s99, 0
	s_add_u32 s96, s96, 0x100
	s_addc_u32 s97, s97, 0
	ds_read_b128 v[160:163], v155 offset:36864
	ds_read_b128 v[164:167], v151 offset:36864
	ds_read_b128 v[168:171], v156 offset:36864
	ds_read_b128 v[172:175], v152 offset:36864
	ds_read_b128 v[176:179], v157 offset:36864
	ds_read_b128 v[180:183], v153 offset:36864
	ds_read_b128 v[184:187], v158 offset:36864
	ds_read_b128 v[188:191], v154 offset:36864
	s_waitcnt lgkmcnt(6)
	v_mfma_f32_16x16x32_bf16 v[0:3], v[160:163], v[164:167], v[0:3]
	s_waitcnt lgkmcnt(4)
	v_mfma_f32_16x16x32_bf16 v[0:3], v[168:171], v[172:175], v[0:3]
	s_waitcnt lgkmcnt(2)
	v_mfma_f32_16x16x32_bf16 v[0:3], v[176:179], v[180:183], v[0:3]
	s_waitcnt lgkmcnt(0)
	v_mfma_f32_16x16x32_bf16 v[0:3], v[184:187], v[188:191], v[0:3]
	s_waitcnt lgkmcnt(0)
	s_barrier
	s_waitcnt vmcnt(14)
	ds_write_b128 v149, v[124:127] offset:36864
	s_waitcnt vmcnt(13)
	ds_write_b128 v149, v[128:131] offset:45056
	s_waitcnt vmcnt(12)
	ds_write_b128 v149, v[132:135] offset:53248
	s_waitcnt vmcnt(11)
	ds_write_b128 v149, v[136:139] offset:61440
	s_waitcnt vmcnt(10)
	ds_write_b128 v150, v[140:143] offset:36864
	global_load_dwordx4 v[104:107], v144, s[98:99]
	global_load_dwordx4 v[108:111], v145, s[98:99]
	global_load_dwordx4 v[112:115], v146, s[98:99]
	global_load_dwordx4 v[116:119], v147, s[98:99]
	global_load_dwordx4 v[120:123], v148, s[96:97]
	s_add_u32 s98, s98, 0x100
	s_addc_u32 s99, s99, 0
	s_add_u32 s96, s96, 0x100
	s_addc_u32 s97, s97, 0
	ds_read_b128 v[160:163], v155
	ds_read_b128 v[164:167], v151
	ds_read_b128 v[168:171], v156
	ds_read_b128 v[172:175], v152
	ds_read_b128 v[176:179], v157
	ds_read_b128 v[180:183], v153
	ds_read_b128 v[184:187], v158
	ds_read_b128 v[188:191], v154
	s_waitcnt lgkmcnt(6)
	v_mfma_f32_16x16x32_bf16 v[0:3], v[160:163], v[164:167], v[0:3]
	s_waitcnt lgkmcnt(4)
	v_mfma_f32_16x16x32_bf16 v[0:3], v[168:171], v[172:175], v[0:3]
	s_waitcnt lgkmcnt(2)
	v_mfma_f32_16x16x32_bf16 v[0:3], v[176:179], v[180:183], v[0:3]
	s_waitcnt lgkmcnt(0)
	v_mfma_f32_16x16x32_bf16 v[0:3], v[184:187], v[188:191], v[0:3]
	s_waitcnt lgkmcnt(0)
	s_barrier
	s_waitcnt vmcnt(14)
	ds_write_b128 v149, v[64:67]
	s_waitcnt vmcnt(13)
	ds_write_b128 v149, v[68:71] offset:8192
	s_waitcnt vmcnt(12)
	ds_write_b128 v149, v[72:75] offset:16384
	s_waitcnt vmcnt(11)
	ds_write_b128 v149, v[76:79] offset:24576
	s_waitcnt vmcnt(10)
	ds_write_b128 v150, v[80:83]
	global_load_dwordx4 v[124:127], v144, s[98:99]
	global_load_dwordx4 v[128:131], v145, s[98:99]
	global_load_dwordx4 v[132:135], v146, s[98:99]
	global_load_dwordx4 v[136:139], v147, s[98:99]
	global_load_dwordx4 v[140:143], v148, s[96:97]
	s_add_u32 s98, s98, 0x100
	s_addc_u32 s99, s99, 0
	s_add_u32 s96, s96, 0x100
	s_addc_u32 s97, s97, 0
	ds_read_b128 v[160:163], v155 offset:36864
	ds_read_b128 v[164:167], v151 offset:36864
	ds_read_b128 v[168:171], v156 offset:36864
	ds_read_b128 v[172:175], v152 offset:36864
	ds_read_b128 v[176:179], v157 offset:36864
	ds_read_b128 v[180:183], v153 offset:36864
	ds_read_b128 v[184:187], v158 offset:36864
	ds_read_b128 v[188:191], v154 offset:36864
	s_waitcnt lgkmcnt(6)
	v_mfma_f32_16x16x32_bf16 v[0:3], v[160:163], v[164:167], v[0:3]
	s_waitcnt lgkmcnt(4)
	v_mfma_f32_16x16x32_bf16 v[0:3], v[168:171], v[172:175], v[0:3]
	s_waitcnt lgkmcnt(2)
	v_mfma_f32_16x16x32_bf16 v[0:3], v[176:179], v[180:183], v[0:3]
	s_waitcnt lgkmcnt(0)
	v_mfma_f32_16x16x32_bf16 v[0:3], v[184:187], v[188:191], v[0:3]
	s_waitcnt lgkmcnt(0)
	s_barrier
	s_waitcnt vmcnt(14)
	ds_write_b128 v149, v[84:87] offset:36864
	s_waitcnt vmcnt(13)
	ds_write_b128 v149, v[88:91] offset:45056
	s_waitcnt vmcnt(12)
	ds_write_b128 v149, v[92:95] offset:53248
	s_waitcnt vmcnt(11)
	ds_write_b128 v149, v[96:99] offset:61440
	s_waitcnt vmcnt(10)
	ds_write_b128 v150, v[100:103] offset:36864
	ds_read_b128 v[160:163], v155
	ds_read_b128 v[164:167], v151
	ds_read_b128 v[168:171], v156
	ds_read_b128 v[172:175], v152
	ds_read_b128 v[176:179], v157
	ds_read_b128 v[180:183], v153
	ds_read_b128 v[184:187], v158
	ds_read_b128 v[188:191], v154
	s_waitcnt lgkmcnt(6)
	v_mfma_f32_16x16x32_bf16 v[0:3], v[160:163], v[164:167], v[0:3]
	s_waitcnt lgkmcnt(4)
	v_mfma_f32_16x16x32_bf16 v[0:3], v[168:171], v[172:175], v[0:3]
	s_waitcnt lgkmcnt(2)
	v_mfma_f32_16x16x32_bf16 v[0:3], v[176:179], v[180:183], v[0:3]
	s_waitcnt lgkmcnt(0)
	v_mfma_f32_16x16x32_bf16 v[0:3], v[184:187], v[188:191], v[0:3]
	s_waitcnt lgkmcnt(0)
	s_barrier
; #define LAS __attribute__((address_space(3)))
; __device__ __forceinline__ unsigned cvt_pk_bf16(float lo, float hi) { f32x2 f = {lo, hi}; bf16x2_t v = __builtin_convertvector(f, bf16x2_t); return __builtin_bit_cast(unsigned, v); }
; template <int MODE>
; __device__ __forceinline__ void sgemm_sample(LAS unsigned char* lds, const bf16_t* A, const bf16_t* Bt, int K, const float* resid, float* out, bf16_t* xb, float* ssq_out, const float* ssq_in) {
;     ...
; #pragma unroll 8
;         for (int ks = 0; ks < K / 32; ++ks) {
;             const bf16x8 a = *(const bf16x8*)(ap + ks * 32); const bf16x8 b = *(const bf16x8*)(bp + ks * 32);
;             acc = __builtin_amdgcn_mfma_f32_16x16x32_bf16(b, a, acc, 0, 0, 0);
;         }
;         if (MODE == 0) {
;             const f32x4 x = *(const f32x4*)(resid + (size_t)(row - NTOKP) * D + col0) + acc;
;             *(f32x4*)(out + (size_t)row * D + col0) = x;
;             if (xb) { u32x2 wv; wv.x = cvt_pk_bf16(x[0], x[1]); wv.y = cvt_pk_bf16(x[2], x[3]); *(u32x2*)(xb + (size_t)row * D + col0) = wv; }
;             if (ssq_out) {
;                 float ss = (x[0] * x[0] + x[1] * x[1]) + (x[2] * x[2] + x[3] * x[3]); ss += __shfl_xor(ss, 16); ss += __shfl_xor(ss, 32);
;                 if (fq == 0) *(LAS float*)(lds + (w * 16 + fr) * 4) = ss;
;                 __syncthreads();
	s_waitcnt vmcnt(9)
	ds_write_b128 v149, v[104:107]
	s_waitcnt vmcnt(8)
	ds_write_b128 v149, v[108:111] offset:8192
	s_waitcnt vmcnt(7)
	ds_write_b128 v149, v[112:115] offset:16384
	s_waitcnt vmcnt(6)
	ds_write_b128 v149, v[116:119] offset:24576
	s_waitcnt vmcnt(5)
	ds_write_b128 v150, v[120:123]
	ds_read_b128 v[160:163], v155 offset:36864
	ds_read_b128 v[164:167], v151 offset:36864
	ds_read_b128 v[168:171], v156 offset:36864
	ds_read_b128 v[172:175], v152 offset:36864
	ds_read_b128 v[176:179], v157 offset:36864
	ds_read_b128 v[180:183], v153 offset:36864
	ds_read_b128 v[184:187], v158 offset:36864
	ds_read_b128 v[188:191], v154 offset:36864
	s_waitcnt lgkmcnt(6)
	v_mfma_f32_16x16x32_bf16 v[0:3], v[160:163], v[164:167], v[0:3]
	s_waitcnt lgkmcnt(4)
	v_mfma_f32_16x16x32_bf16 v[0:3], v[168:171], v[172:175], v[0:3]
	s_waitcnt lgkmcnt(2)
	v_mfma_f32_16x16x32_bf16 v[0:3], v[176:179], v[180:183], v[0:3]
	s_waitcnt lgkmcnt(0)
	v_mfma_f32_16x16x32_bf16 v[0:3], v[184:187], v[188:191], v[0:3]
	s_waitcnt lgkmcnt(0)
	s_barrier
	s_waitcnt vmcnt(4)
	ds_write_b128 v149, v[124:127] offset:36864
	s_waitcnt vmcnt(3)
	ds_write_b128 v149, v[128:131] offset:45056
	s_waitcnt vmcnt(2)
	ds_write_b128 v149, v[132:135] offset:53248
	s_waitcnt vmcnt(1)
	ds_write_b128 v149, v[136:139] offset:61440
	s_waitcnt vmcnt(0)
	ds_write_b128 v150, v[140:143] offset:36864
	ds_read_b128 v[160:163], v155
	ds_read_b128 v[164:167], v151
	ds_read_b128 v[168:171], v156
	ds_read_b128 v[172:175], v152
	ds_read_b128 v[176:179], v157
	ds_read_b128 v[180:183], v153
	ds_read_b128 v[184:187], v158
	ds_read_b128 v[188:191], v154
	s_waitcnt lgkmcnt(6)
	v_mfma_f32_16x16x32_bf16 v[0:3], v[160:163], v[164:167], v[0:3]
	s_waitcnt lgkmcnt(4)
	v_mfma_f32_16x16x32_bf16 v[0:3], v[168:171], v[172:175], v[0:3]
	s_waitcnt lgkmcnt(2)
	v_mfma_f32_16x16x32_bf16 v[0:3], v[176:179], v[180:183], v[0:3]
	s_waitcnt lgkmcnt(0)
	v_mfma_f32_16x16x32_bf16 v[0:3], v[184:187], v[188:191], v[0:3]
	s_waitcnt lgkmcnt(0)
	s_barrier
	ds_read_b128 v[160:163], v155 offset:36864
	ds_read_b128 v[164:167], v151 offset:36864
	ds_read_b128 v[168:171], v156 offset:36864
	ds_read_b128 v[172:175], v152 offset:36864
	ds_read_b128 v[176:179], v157 offset:36864
	ds_read_b128 v[180:183], v153 offset:36864
	ds_read_b128 v[184:187], v158 offset:36864
	ds_read_b128 v[188:191], v154 offset:36864
	s_waitcnt lgkmcnt(6)
	v_mfma_f32_16x16x32_bf16 v[0:3], v[160:163], v[164:167], v[0:3]
	s_waitcnt lgkmcnt(4)
	v_mfma_f32_16x16x32_bf16 v[0:3], v[168:171], v[172:175], v[0:3]
	s_waitcnt lgkmcnt(2)
	v_mfma_f32_16x16x32_bf16 v[0:3], v[176:179], v[180:183], v[0:3]
	s_waitcnt lgkmcnt(0)
	v_mfma_f32_16x16x32_bf16 v[0:3], v[184:187], v[188:191], v[0:3]
	s_nop 7
	s_branch .Lsgx0_done
.LBB0_895:
	v_lshl_add_u64 v[24:25], v[14:15], 0, s[16:17]
	v_add_co_u32_e32 v60, vcc, 0x15780000, v24
	v_lshl_add_u64 v[26:27], v[10:11], 0, s[16:17]
	s_nop 0
	v_addc_co_u32_e32 v61, vcc, 0, v25, vcc
	v_add_co_u32_e32 v62, vcc, 0x840000, v26
	s_add_u32 s16, s16, 0x200
	s_nop 0
	v_addc_co_u32_e32 v63, vcc, 0, v27, vcc
	global_load_dwordx4 v[24:27], v[60:61], off
	global_load_dwordx4 v[28:31], v[60:61], off offset:64
	global_load_dwordx4 v[32:35], v[60:61], off offset:128
	global_load_dwordx4 v[36:39], v[60:61], off offset:192
	global_load_dwordx4 v[40:43], v[60:61], off offset:256
	global_load_dwordx4 v[44:47], v[62:63], off
	global_load_dwordx4 v[48:51], v[62:63], off offset:64
	global_load_dwordx4 v[52:55], v[62:63], off offset:128
	global_load_dwordx4 v[56:59], v[62:63], off offset:192
	s_addc_u32 s17, s17, 0
	s_cmpk_eq_i32 s16, 0x800
	s_waitcnt vmcnt(3)
	v_mfma_f32_16x16x32_bf16 v[0:3], v[44:47], v[24:27], v[0:3]
	global_load_dwordx4 v[24:27], v[62:63], off offset:256
	s_waitcnt vmcnt(3)
	v_mfma_f32_16x16x32_bf16 v[0:3], v[48:51], v[28:31], v[0:3]
	global_load_dwordx4 v[28:31], v[62:63], off offset:320
	s_waitcnt vmcnt(3)
	v_mfma_f32_16x16x32_bf16 v[0:3], v[52:55], v[32:35], v[0:3]
	global_load_dwordx4 v[32:35], v[60:61], off offset:320
	s_waitcnt vmcnt(3)
	v_mfma_f32_16x16x32_bf16 v[0:3], v[56:59], v[36:39], v[0:3]
	global_load_dwordx4 v[36:39], v[62:63], off offset:384
	global_load_dwordx4 v[44:47], v[60:61], off offset:384
	s_waitcnt vmcnt(4)
	v_mfma_f32_16x16x32_bf16 v[0:3], v[24:27], v[40:43], v[0:3]
	global_load_dwordx4 v[24:27], v[62:63], off offset:448
	s_waitcnt vmcnt(3)
	v_mfma_f32_16x16x32_bf16 v[0:3], v[28:31], v[32:35], v[0:3]
	global_load_dwordx4 v[28:31], v[60:61], off offset:448
	s_waitcnt vmcnt(2)
	v_mfma_f32_16x16x32_bf16 v[0:3], v[36:39], v[44:47], v[0:3]
	s_waitcnt vmcnt(0)
	v_mfma_f32_16x16x32_bf16 v[0:3], v[24:27], v[28:31], v[0:3]
	s_cbranch_scc0 .LBB0_895
	s_and_b32 s18, s3, 63
	v_lshl_or_b32 v24, s18, 4, v18
	v_lshlrev_b64 v[14:15], 12, v[12:13]
	v_lshl_add_u64 v[10:11], s[40:41], 0, v[14:15]
	v_lshlrev_b32_e32 v4, 2, v24
	v_lshl_add_u64 v[10:11], v[10:11], 0, v[4:5]
	v_add_co_u32_e32 v10, vcc, 0xf8000000, v10
	v_lshl_add_u64 v[14:15], s[90:91], 0, v[14:15]
	s_nop 0
	v_addc_co_u32_e32 v11, vcc, -1, v11, vcc
	global_load_dwordx4 v[10:13], v[10:11], off
.Lsgx0_done:
	s_waitcnt vmcnt(0)
	v_pk_add_f32 v[2:3], v[2:3], v[12:13]
	v_pk_add_f32 v[0:1], v[0:1], v[10:11]
	v_mul_f32_e32 v11, v3, v3
	v_mul_f32_e32 v10, v1, v1
	v_fmac_f32_e32 v10, v0, v0
	v_fmac_f32_e32 v11, v2, v2
	v_add_f32_e32 v12, v10, v11
	ds_bpermute_b32 v13, v19, v12
	v_lshl_add_u64 v[10:11], v[14:15], 0, v[4:5]
	global_store_dwordx4 v[10:11], v[0:3], off
	v_cvt_pk_bf16_f32 v10, v0, v1
	v_cvt_pk_bf16_f32 v11, v2, v3
	s_waitcnt lgkmcnt(0)
	v_add_f32_e32 v0, v12, v13
	ds_bpermute_b32 v1, v20, v0
	v_lshl_add_u64 v[2:3], s[10:11], 0, v[8:9]
	v_lshlrev_b32_e32 v4, 1, v24
	v_lshl_add_u64 v[2:3], v[2:3], 0, v[4:5]
	global_store_dwordx2 v[2:3], v[10:11], off
	s_and_saveexec_b64 s[16:17], s[0:1]
	s_cbranch_execz .LBB0_898
	s_waitcnt lgkmcnt(0)
	v_add_f32_e32 v0, v0, v1
	ds_write_b32 v22, v0

; template <int MODE>
; __device__ __forceinline__ void sgemm_sample(LAS unsigned char* lds, const bf16_t* A, const bf16_t* Bt, int K, const float* resid, float* out, bf16_t* xb, float* ssq_out, const float* ssq_in) {
;     ...
;     for (int uu = u; uu < 2048; uu += gridDim.x * 8) {
;         const int rt = uu >> 6, ct = uu & 63; const int row = NTOKP + rt * 16 + fr, col0 = ct * 16 + fq * 4;
;         const bf16_t* ap = A + (size_t)row * K + fq * 8; const bf16_t* bp = Bt + (size_t)(ct * 16 + fr) * K + fq * 8;
;         f32x4 acc = {0.f, 0.f, 0.f, 0.f};
; #pragma unroll 8
;         for (int ks = 0; ks < K / 32; ++ks) {
;             const bf16x8 a = *(const bf16x8*)(ap + ks * 32); const bf16x8 b = *(const bf16x8*)(bp + ks * 32);
;             acc = __builtin_amdgcn_mfma_f32_16x16x32_bf16(b, a, acc, 0, 0, 0);
;         }
;     ...
;             const float sc = rs_from_parts(ssq_in + (size_t)row * 16) * 0.0625f;
.LBB0_999:
	s_lshl_b32 s0, s7, 11
	s_and_b32 s0, s0, 0x1f8000
	v_lshl_or_b32 v4, v18, 1, s0
	s_ashr_i32 s0, s3, 2
	s_and_b32 s0, s0, -16
	v_add_u32_e32 v10, s0, v16
	v_ashrrev_i32_e32 v11, 31, v10
	v_lshlrev_b64 v[8:9], 11, v[10:11]
	v_lshl_add_u64 v[12:13], v[6:7], 0, v[4:5]
	v_lshl_add_u64 v[14:15], v[6:7], 0, v[8:9]
	s_mov_b64 s[0:1], 0
	v_mov_b32_e32 v0, 0
	v_mov_b32_e32 v1, v5
	v_mov_b32_e32 v2, v5
	v_mov_b32_e32 v3, v5
	s_cmpk_lg_i32 s34, 0x100
	s_cbranch_scc1 .LBB0_1000
	s_waitcnt vmcnt(0)
	v_lshlrev_b64 v[10:11], 6, v[10:11]
	v_lshl_add_u64 v[14:15], s[4:5], 0, v[10:11]
	global_load_dwordx4 v[10:13], v[14:15], off
	global_load_dwordx4 v[20:23], v[14:15], off offset:16
	global_load_dwordx4 v[24:27], v[14:15], off offset:32
	global_load_dwordx4 v[28:31], v[14:15], off offset:48
	s_lshr_b32 s100, s2, 3
	s_lshl_b32 s100, s100, 4
	s_add_i32 s100, s100, 0x8000
	s_mul_i32 s100, s100, 0x800
	s_add_u32 s96, s92, s100
	s_addc_u32 s97, s93, 0
	s_add_u32 s96, s96, 0xa4c0000
	s_addc_u32 s97, s97, 0
	s_and_b32 s100, s2, 7
	s_lshl_b32 s100, s100, 7
	s_mul_i32 s100, s100, 0x800
	s_add_u32 s98, s92, s100
	s_addc_u32 s99, s93, 0
	s_add_u32 s98, s98, 0xa40000
	s_addc_u32 s99, s99, 0
	v_lshrrev_b32_e32 v192, 4, v200
	v_and_b32_e32 v193, 15, v200
	v_and_b32_e32 v194, 15, v192
	v_xor_b32_e32 v193, v193, v194
	v_lshlrev_b32_e32 v193, 4, v193
	s_mov_b32 s100, 0x800
	v_mad_u32_u24 v144, v192, s100, v193
	v_add_u32_e32 v145, 0x10000, v144
	v_add_u32_e32 v146, 0x20000, v144
	v_add_u32_e32 v147, 0x30000, v144
	v_mad_u32_u24 v148, v194, s100, v193
	v_lshlrev_b32_e32 v149, 4, v200
	v_add_u32_e32 v149, 1024, v149
	v_and_b32_e32 v150, 0xff, v200
	v_lshlrev_b32_e32 v150, 4, v150
	v_add_u32_e32 v150, 33792, v150
	v_and_b32_e32 v192, 15, v200
	v_bfe_u32 v193, v200, 4, 2
	v_and_b32_e32 v194, 3, v192
	v_xor_b32_e32 v193, v193, v194
	v_lshlrev_b32_e32 v193, 4, v193
	v_lshrrev_b32_e32 v194, 2, v192
	v_lshl_add_u32 v193, v194, 6, v193
	v_lshl_add_u32 v193, v192, 8, v193
	v_add_u32_e32 v151, 33792, v193
	v_lshrrev_b32_e32 v194, 6, v200
	v_lshlrev_b32_e32 v194, 12, v194
	v_add_u32_e32 v155, v193, v194
	v_add_u32_e32 v155, 1024, v155
	v_xor_b32_e32 v152, 0x40, v151
	v_xor_b32_e32 v156, 0x40, v155
	v_xor_b32_e32 v153, 0x80, v151
	v_xor_b32_e32 v157, 0x80, v155
	v_xor_b32_e32 v154, 0xc0, v151
	v_xor_b32_e32 v158, 0xc0, v155
	global_load_dwordx4 v[64:67], v144, s[98:99]
	global_load_dwordx4 v[68:71], v145, s[98:99]
	global_load_dwordx4 v[72:75], v146, s[98:99]
	global_load_dwordx4 v[76:79], v147, s[98:99]
	global_load_dwordx4 v[80:83], v148, s[96:97]
	s_add_u32 s98, s98, 0x100
	s_addc_u32 s99, s99, 0
	s_add_u32 s96, s96, 0x100
	s_addc_u32 s97, s97, 0
	global_load_dwordx4 v[84:87], v144, s[98:99]
	global_load_dwordx4 v[88:91], v145, s[98:99]
	global_load_dwordx4 v[92:95], v146, s[98:99]
	global_load_dwordx4 v[96:99], v147, s[98:99]
	global_load_dwordx4 v[100:103], v148, s[96:97]
	s_add_u32 s98, s98, 0x100
	s_addc_u32 s99, s99, 0
	s_add_u32 s96, s96, 0x100
	s_addc_u32 s97, s97, 0
	global_load_dwordx4 v[104:107], v144, s[98:99]
	global_load_dwordx4 v[108:111], v145, s[98:99]
	global_load_dwordx4 v[112:115], v146, s[98:99]
	global_load_dwordx4 v[116:119], v147, s[98:99]
	global_load_dwordx4 v[120:123], v148, s[96:97]
	s_add_u32 s98, s98, 0x100
	s_addc_u32 s99, s99, 0
	s_add_u32 s96, s96, 0x100
	s_addc_u32 s97, s97, 0
	global_load_dwordx4 v[124:127], v144, s[98:99]
	global_load_dwordx4 v[128:131], v145, s[98:99]
	global_load_dwordx4 v[132:135], v146, s[98:99]
	global_load_dwordx4 v[136:139], v147, s[98:99]
	global_load_dwordx4 v[140:143], v148, s[96:97]
	s_add_u32 s98, s98, 0x100
	s_addc_u32 s99, s99, 0
	s_add_u32 s96, s96, 0x100
	s_addc_u32 s97, s97, 0
	s_waitcnt vmcnt(19)
	ds_write_b128 v149, v[64:67]
	s_waitcnt vmcnt(18)
	ds_write_b128 v149, v[68:71] offset:8192
	s_waitcnt vmcnt(17)
	ds_write_b128 v149, v[72:75] offset:16384
	s_waitcnt vmcnt(16)
	ds_write_b128 v149, v[76:79] offset:24576
	s_waitcnt vmcnt(15)
	ds_write_b128 v150, v[80:83]
	s_waitcnt lgkmcnt(0)
	s_barrier
	s_waitcnt vmcnt(14)
	ds_write_b128 v149, v[84:87] offset:36864
	s_waitcnt vmcnt(13)
	ds_write_b128 v149, v[88:91] offset:45056
	s_waitcnt vmcnt(12)
	ds_write_b128 v149, v[92:95] offset:53248
	s_waitcnt vmcnt(11)
	ds_write_b128 v149, v[96:99] offset:61440
	s_waitcnt vmcnt(10)
	ds_write_b128 v150, v[100:103] offset:36864
	global_load_dwordx4 v[64:67], v144, s[98:99]
	global_load_dwordx4 v[68:71], v145, s[98:99]
	global_load_dwordx4 v[72:75], v146, s[98:99]
	global_load_dwordx4 v[76:79], v147, s[98:99]
	global_load_dwordx4 v[80:83], v148, s[96:97]
	s_add_u32 s98, s98, 0x100
	s_addc_u32 s99, s99, 0
	s_add_u32 s96, s96, 0x100
	s_addc_u32 s97, s97, 0
	ds_read_b128 v[160:163], v155
	ds_read_b128 v[164:167], v151
	ds_read_b128 v[168:171], v156
	ds_read_b128 v[172:175], v152
	ds_read_b128 v[176:179], v157
	ds_read_b128 v[180:183], v153
	ds_read_b128 v[184:187], v158
	ds_read_b128 v[188:191], v154
	s_waitcnt lgkmcnt(6)
	v_mfma_f32_16x16x32_bf16 v[0:3], v[160:163], v[164:167], v[0:3]
	s_waitcnt lgkmcnt(4)
	v_mfma_f32_16x16x32_bf16 v[0:3], v[168:171], v[172:175], v[0:3]
	s_waitcnt lgkmcnt(2)
	v_mfma_f32_16x16x32_bf16 v[0:3], v[176:179], v[180:183], v[0:3]
	s_waitcnt lgkmcnt(0)
	v_mfma_f32_16x16x32_bf16 v[0:3], v[184:187], v[188:191], v[0:3]
	s_waitcnt lgkmcnt(0)
	s_barrier
; template <int MODE>
; __device__ __forceinline__ void sgemm_sample(LAS unsigned char* lds, const bf16_t* A, const bf16_t* Bt, int K, const float* resid, float* out, bf16_t* xb, float* ssq_out, const float* ssq_in) {
;     ...
; #pragma unroll 8
;         for (int ks = 0; ks < K / 32; ++ks) {
;             const bf16x8 a = *(const bf16x8*)(ap + ks * 32); const bf16x8 b = *(const bf16x8*)(bp + ks * 32);
;             acc = __builtin_amdgcn_mfma_f32_16x16x32_bf16(b, a, acc, 0, 0, 0);
;         }
	s_waitcnt vmcnt(14)
	ds_write_b128 v149, v[104:107]
	s_waitcnt vmcnt(13)
	ds_write_b128 v149, v[108:111] offset:8192
	s_waitcnt vmcnt(12)
	ds_write_b128 v149, v[112:115] offset:16384
	s_waitcnt vmcnt(11)
	ds_write_b128 v149, v[116:119] offset:24576
	s_waitcnt vmcnt(10)
	ds_write_b128 v150, v[120:123]
	global_load_dwordx4 v[84:87], v144, s[98:99]
	global_load_dwordx4 v[88:91], v145, s[98:99]
	global_load_dwordx4 v[92:95], v146, s[98:99]
	global_load_dwordx4 v[96:99], v147, s[98:99]
	global_load_dwordx4 v[100:103], v148, s[96:97]
	s_add_u32 s98, s98, 0x100
	s_addc_u32 s99, s99, 0
	s_add_u32 s96, s96, 0x100
	s_addc_u32 s97, s97, 0
	ds_read_b128 v[160:163], v155 offset:36864
	ds_read_b128 v[164:167], v151 offset:36864
	ds_read_b128 v[168:171], v156 offset:36864
	ds_read_b128 v[172:175], v152 offset:36864
	ds_read_b128 v[176:179], v157 offset:36864
	ds_read_b128 v[180:183], v153 offset:36864
	ds_read_b128 v[184:187], v158 offset:36864
	ds_read_b128 v[188:191], v154 offset:36864
	s_waitcnt lgkmcnt(6)
	v_mfma_f32_16x16x32_bf16 v[0:3], v[160:163], v[164:167], v[0:3]
	s_waitcnt lgkmcnt(4)
	v_mfma_f32_16x16x32_bf16 v[0:3], v[168:171], v[172:175], v[0:3]
	s_waitcnt lgkmcnt(2)
	v_mfma_f32_16x16x32_bf16 v[0:3], v[176:179], v[180:183], v[0:3]
	s_waitcnt lgkmcnt(0)
	v_mfma_f32_16x16x32_bf16 v[0:3], v[184:187], v[188:191], v[0:3]
	s_waitcnt lgkmcnt(0)
	s_barrier
	s_waitcnt vmcnt(14)
	ds_write_b128 v149, v[124:127] offset:36864
	s_waitcnt vmcnt(13)
	ds_write_b128 v149, v[128:131] offset:45056
	s_waitcnt vmcnt(12)
	ds_write_b128 v149, v[132:135] offset:53248
	s_waitcnt vmcnt(11)
	ds_write_b128 v149, v[136:139] offset:61440
	s_waitcnt vmcnt(10)
	ds_write_b128 v150, v[140:143] offset:36864
	global_load_dwordx4 v[104:107], v144, s[98:99]
	global_load_dwordx4 v[108:111], v145, s[98:99]
	global_load_dwordx4 v[112:115], v146, s[98:99]
	global_load_dwordx4 v[116:119], v147, s[98:99]
	global_load_dwordx4 v[120:123], v148, s[96:97]
	s_add_u32 s98, s98, 0x100
	s_addc_u32 s99, s99, 0
	s_add_u32 s96, s96, 0x100
	s_addc_u32 s97, s97, 0
	ds_read_b128 v[160:163], v155
	ds_read_b128 v[164:167], v151
	ds_read_b128 v[168:171], v156
	ds_read_b128 v[172:175], v152
	ds_read_b128 v[176:179], v157
	ds_read_b128 v[180:183], v153
	ds_read_b128 v[184:187], v158
	ds_read_b128 v[188:191], v154
	s_waitcnt lgkmcnt(6)
	v_mfma_f32_16x16x32_bf16 v[0:3], v[160:163], v[164:167], v[0:3]
	s_waitcnt lgkmcnt(4)
	v_mfma_f32_16x16x32_bf16 v[0:3], v[168:171], v[172:175], v[0:3]
	s_waitcnt lgkmcnt(2)
	v_mfma_f32_16x16x32_bf16 v[0:3], v[176:179], v[180:183], v[0:3]
	s_waitcnt lgkmcnt(0)
	v_mfma_f32_16x16x32_bf16 v[0:3], v[184:187], v[188:191], v[0:3]
	s_waitcnt lgkmcnt(0)
	s_barrier
	s_waitcnt vmcnt(14)
	ds_write_b128 v149, v[64:67]
	s_waitcnt vmcnt(13)
	ds_write_b128 v149, v[68:71] offset:8192
	s_waitcnt vmcnt(12)
	ds_write_b128 v149, v[72:75] offset:16384
	s_waitcnt vmcnt(11)
	ds_write_b128 v149, v[76:79] offset:24576
	s_waitcnt vmcnt(10)
	ds_write_b128 v150, v[80:83]
	global_load_dwordx4 v[124:127], v144, s[98:99]
	global_load_dwordx4 v[128:131], v145, s[98:99]
	global_load_dwordx4 v[132:135], v146, s[98:99]
	global_load_dwordx4 v[136:139], v147, s[98:99]
	global_load_dwordx4 v[140:143], v148, s[96:97]
	s_add_u32 s98, s98, 0x100
	s_addc_u32 s99, s99, 0
	s_add_u32 s96, s96, 0x100
	s_addc_u32 s97, s97, 0
	ds_read_b128 v[160:163], v155 offset:36864
	ds_read_b128 v[164:167], v151 offset:36864
	ds_read_b128 v[168:171], v156 offset:36864
	ds_read_b128 v[172:175], v152 offset:36864
	ds_read_b128 v[176:179], v157 offset:36864
	ds_read_b128 v[180:183], v153 offset:36864
	ds_read_b128 v[184:187], v158 offset:36864
	ds_read_b128 v[188:191], v154 offset:36864
	s_waitcnt lgkmcnt(6)
	v_mfma_f32_16x16x32_bf16 v[0:3], v[160:163], v[164:167], v[0:3]
	s_waitcnt lgkmcnt(4)
	v_mfma_f32_16x16x32_bf16 v[0:3], v[168:171], v[172:175], v[0:3]
	s_waitcnt lgkmcnt(2)
	v_mfma_f32_16x16x32_bf16 v[0:3], v[176:179], v[180:183], v[0:3]
	s_waitcnt lgkmcnt(0)
	v_mfma_f32_16x16x32_bf16 v[0:3], v[184:187], v[188:191], v[0:3]
	s_waitcnt lgkmcnt(0)
	s_barrier
	s_waitcnt vmcnt(14)
	ds_write_b128 v149, v[84:87] offset:36864
	s_waitcnt vmcnt(13)
	ds_write_b128 v149, v[88:91] offset:45056
	s_waitcnt vmcnt(12)
	ds_write_b128 v149, v[92:95] offset:53248
	s_waitcnt vmcnt(11)
	ds_write_b128 v149, v[96:99] offset:61440
	s_waitcnt vmcnt(10)
	ds_write_b128 v150, v[100:103] offset:36864
	ds_read_b128 v[160:163], v155
	ds_read_b128 v[164:167], v151
	ds_read_b128 v[168:171], v156
	ds_read_b128 v[172:175], v152
	ds_read_b128 v[176:179], v157
	ds_read_b128 v[180:183], v153
	ds_read_b128 v[184:187], v158
	ds_read_b128 v[188:191], v154
	s_waitcnt lgkmcnt(6)
	v_mfma_f32_16x16x32_bf16 v[0:3], v[160:163], v[164:167], v[0:3]
	s_waitcnt lgkmcnt(4)
	v_mfma_f32_16x16x32_bf16 v[0:3], v[168:171], v[172:175], v[0:3]
	s_waitcnt lgkmcnt(2)
	v_mfma_f32_16x16x32_bf16 v[0:3], v[176:179], v[180:183], v[0:3]
	s_waitcnt lgkmcnt(0)
	v_mfma_f32_16x16x32_bf16 v[0:3], v[184:187], v[188:191], v[0:3]
	s_waitcnt lgkmcnt(0)
	s_barrier
	s_waitcnt vmcnt(9)
	ds_write_b128 v149, v[104:107]
	s_waitcnt vmcnt(8)
	ds_write_b128 v149, v[108:111] offset:8192
	s_waitcnt vmcnt(7)
	ds_write_b128 v149, v[112:115] offset:16384
	s_waitcnt vmcnt(6)
	ds_write_b128 v149, v[116:119] offset:24576
	s_waitcnt vmcnt(5)
	ds_write_b128 v150, v[120:123]
	ds_read_b128 v[160:163], v155 offset:36864
	ds_read_b128 v[164:167], v151 offset:36864
	ds_read_b128 v[168:171], v156 offset:36864
	ds_read_b128 v[172:175], v152 offset:36864
	ds_read_b128 v[176:179], v157 offset:36864
	ds_read_b128 v[180:183], v153 offset:36864
	ds_read_b128 v[184:187], v158 offset:36864
	ds_read_b128 v[188:191], v154 offset:36864
	s_waitcnt lgkmcnt(6)
	v_mfma_f32_16x16x32_bf16 v[0:3], v[160:163], v[164:167], v[0:3]
	s_waitcnt lgkmcnt(4)
	v_mfma_f32_16x16x32_bf16 v[0:3], v[168:171], v[172:175], v[0:3]
	s_waitcnt lgkmcnt(2)
	v_mfma_f32_16x16x32_bf16 v[0:3], v[176:179], v[180:183], v[0:3]
	s_waitcnt lgkmcnt(0)
	v_mfma_f32_16x16x32_bf16 v[0:3], v[184:187], v[188:191], v[0:3]
	s_waitcnt lgkmcnt(0)
	s_barrier
; #define LAS __attribute__((address_space(3)))
; __device__ __forceinline__ unsigned cvt_pk_bf16(float lo, float hi) { f32x2 f = {lo, hi}; bf16x2_t v = __builtin_convertvector(f, bf16x2_t); return __builtin_bit_cast(unsigned, v); }
; template <int MODE>
; __device__ __forceinline__ void sgemm_sample(LAS unsigned char* lds, const bf16_t* A, const bf16_t* Bt, int K, const float* resid, float* out, bf16_t* xb, float* ssq_out, const float* ssq_in) {
;     ...
; #pragma unroll 8
;         for (int ks = 0; ks < K / 32; ++ks) {
;             const bf16x8 a = *(const bf16x8*)(ap + ks * 32); const bf16x8 b = *(const bf16x8*)(bp + ks * 32);
;             acc = __builtin_amdgcn_mfma_f32_16x16x32_bf16(b, a, acc, 0, 0, 0);
;         }
;         if (MODE == 0) {
;             const f32x4 x = *(const f32x4*)(resid + (size_t)(row - NTOKP) * D + col0) + acc;
;             *(f32x4*)(out + (size_t)row * D + col0) = x;
;             if (xb) { u32x2 wv; wv.x = cvt_pk_bf16(x[0], x[1]); wv.y = cvt_pk_bf16(x[2], x[3]); *(u32x2*)(xb + (size_t)row * D + col0) = wv; }
;             if (ssq_out) {
;                 float ss = (x[0] * x[0] + x[1] * x[1]) + (x[2] * x[2] + x[3] * x[3]); ss += __shfl_xor(ss, 16); ss += __shfl_xor(ss, 32);
;                 if (fq == 0) *(LAS float*)(lds + (w * 16 + fr) * 4) = ss;
;                 __syncthreads();
;                 if (tid < 16) { float t = 0.f;
; #pragma unroll
;                     for (int i = 0; i < 8; ++i) t += *(const LAS float*)(lds + (i * 16 + tid) * 4);
;                     const int g = (uu & 63) >> 3; float* sp = ssq_out + (size_t)(NTOKP + rt * 16 + tid) * 16; sp[g] = t; sp[8 + g] = 0.f; }
;                 __syncthreads();
;             }
;         } else {
;             const float sc = rs_from_parts(ssq_in + (size_t)row * 16) * 0.0625f;
;             u32x2 wv; wv.x = cvt_pk_bf16(acc[0] * sc, acc[1] * sc); wv.y = cvt_pk_bf16(acc[2] * sc, acc[3] * sc); *(u32x2*)(xb + (size_t)row * D + col0) = wv;
	s_waitcnt vmcnt(4)
	ds_write_b128 v149, v[124:127] offset:36864
	s_waitcnt vmcnt(3)
	ds_write_b128 v149, v[128:131] offset:45056
	s_waitcnt vmcnt(2)
	ds_write_b128 v149, v[132:135] offset:53248
	s_waitcnt vmcnt(1)
	ds_write_b128 v149, v[136:139] offset:61440
	s_waitcnt vmcnt(0)
	ds_write_b128 v150, v[140:143] offset:36864
	ds_read_b128 v[160:163], v155
	ds_read_b128 v[164:167], v151
	ds_read_b128 v[168:171], v156
	ds_read_b128 v[172:175], v152
	ds_read_b128 v[176:179], v157
	ds_read_b128 v[180:183], v153
	ds_read_b128 v[184:187], v158
	ds_read_b128 v[188:191], v154
	s_waitcnt lgkmcnt(6)
	v_mfma_f32_16x16x32_bf16 v[0:3], v[160:163], v[164:167], v[0:3]
	s_waitcnt lgkmcnt(4)
	v_mfma_f32_16x16x32_bf16 v[0:3], v[168:171], v[172:175], v[0:3]
	s_waitcnt lgkmcnt(2)
	v_mfma_f32_16x16x32_bf16 v[0:3], v[176:179], v[180:183], v[0:3]
	s_waitcnt lgkmcnt(0)
	v_mfma_f32_16x16x32_bf16 v[0:3], v[184:187], v[188:191], v[0:3]
	s_waitcnt lgkmcnt(0)
	s_barrier
	ds_read_b128 v[160:163], v155 offset:36864
	ds_read_b128 v[164:167], v151 offset:36864
	ds_read_b128 v[168:171], v156 offset:36864
	ds_read_b128 v[172:175], v152 offset:36864
	ds_read_b128 v[176:179], v157 offset:36864
	ds_read_b128 v[180:183], v153 offset:36864
	ds_read_b128 v[184:187], v158 offset:36864
	ds_read_b128 v[188:191], v154 offset:36864
	s_waitcnt lgkmcnt(6)
	v_mfma_f32_16x16x32_bf16 v[0:3], v[160:163], v[164:167], v[0:3]
	s_waitcnt lgkmcnt(4)
	v_mfma_f32_16x16x32_bf16 v[0:3], v[168:171], v[172:175], v[0:3]
	s_waitcnt lgkmcnt(2)
	v_mfma_f32_16x16x32_bf16 v[0:3], v[176:179], v[180:183], v[0:3]
	s_waitcnt lgkmcnt(0)
	v_mfma_f32_16x16x32_bf16 v[0:3], v[184:187], v[188:191], v[0:3]
	s_nop 7
	s_branch .Lsgx1_done
.LBB0_1000:
	v_lshl_add_u64 v[20:21], v[14:15], 0, s[0:1]
	v_add_co_u32_e32 v56, vcc, 0xa4c0000, v20
	v_lshl_add_u64 v[22:23], v[12:13], 0, s[0:1]
	s_nop 0
	v_addc_co_u32_e32 v57, vcc, 0, v21, vcc
	v_add_co_u32_e32 v58, vcc, 0xa40000, v22
	s_add_u32 s0, s0, 0x200
	s_nop 0
	v_addc_co_u32_e32 v59, vcc, 0, v23, vcc
	global_load_dwordx4 v[20:23], v[56:57], off
	global_load_dwordx4 v[24:27], v[56:57], off offset:64
	global_load_dwordx4 v[28:31], v[56:57], off offset:128
	global_load_dwordx4 v[32:35], v[56:57], off offset:192
	global_load_dwordx4 v[36:39], v[56:57], off offset:256
	global_load_dwordx4 v[40:43], v[58:59], off
	global_load_dwordx4 v[44:47], v[58:59], off offset:64
	global_load_dwordx4 v[48:51], v[58:59], off offset:128
	global_load_dwordx4 v[52:55], v[58:59], off offset:192
	s_addc_u32 s1, s1, 0
	s_cmpk_eq_i32 s0, 0x800
	s_waitcnt vmcnt(3)
	v_mfma_f32_16x16x32_bf16 v[0:3], v[40:43], v[20:23], v[0:3]
	global_load_dwordx4 v[20:23], v[58:59], off offset:256
	s_waitcnt vmcnt(3)
	v_mfma_f32_16x16x32_bf16 v[0:3], v[44:47], v[24:27], v[0:3]
	global_load_dwordx4 v[24:27], v[58:59], off offset:320
	s_waitcnt vmcnt(3)
	v_mfma_f32_16x16x32_bf16 v[0:3], v[48:51], v[28:31], v[0:3]
	global_load_dwordx4 v[28:31], v[56:57], off offset:320
	s_waitcnt vmcnt(3)
	v_mfma_f32_16x16x32_bf16 v[0:3], v[52:55], v[32:35], v[0:3]
	global_load_dwordx4 v[32:35], v[58:59], off offset:384
	global_load_dwordx4 v[40:43], v[56:57], off offset:384
	s_waitcnt vmcnt(4)
	v_mfma_f32_16x16x32_bf16 v[0:3], v[20:23], v[36:39], v[0:3]
	global_load_dwordx4 v[20:23], v[58:59], off offset:448
	s_waitcnt vmcnt(3)
	v_mfma_f32_16x16x32_bf16 v[0:3], v[24:27], v[28:31], v[0:3]
	global_load_dwordx4 v[24:27], v[56:57], off offset:448
	s_waitcnt vmcnt(2)
	v_mfma_f32_16x16x32_bf16 v[0:3], v[32:35], v[40:43], v[0:3]
	s_waitcnt vmcnt(0)
	v_mfma_f32_16x16x32_bf16 v[0:3], v[20:23], v[24:27], v[0:3]
	s_cbranch_scc0 .LBB0_1000
	v_lshlrev_b64 v[10:11], 6, v[10:11]
	v_lshl_add_u64 v[14:15], s[4:5], 0, v[10:11]
	global_load_dwordx4 v[10:13], v[14:15], off
	global_load_dwordx4 v[20:23], v[14:15], off offset:16
	global_load_dwordx4 v[24:27], v[14:15], off offset:32
	global_load_dwordx4 v[28:31], v[14:15], off offset:48
.Lsgx1_done:
	s_lshl_b32 s0, s3, 4
	s_and_b32 s0, s0, 0x3f0
	v_lshl_add_u64 v[8:9], s[10:11], 0, v[8:9]
	s_add_i32 s3, s3, s6
	s_add_i32 s7, s7, s12
	s_cmpk_gt_i32 s3, 0x7ff
	s_waitcnt vmcnt(3)
	v_mov_b32_e32 v14, v11
	v_mov_b32_e32 v15, v12
	v_mov_b32_e32 v11, v13
	s_waitcnt vmcnt(2)
	v_mov_b32_e32 v12, v21
	v_mov_b32_e32 v13, v22
	v_mov_b32_e32 v21, v23
	v_pk_add_f32 v[10:11], v[14:15], v[10:11]
	v_pk_add_f32 v[12:13], v[12:13], v[20:21]
	v_pk_add_f32 v[10:11], v[10:11], v[10:11] op_sel:[0,1] op_sel_hi:[1,0]
	v_pk_add_f32 v[12:13], v[12:13], v[12:13] op_sel:[0,1] op_sel_hi:[1,0]
	s_waitcnt vmcnt(1)
	v_add_f32_e32 v22, v24, v25
	v_add_f32_e32 v24, v26, v27
	s_waitcnt vmcnt(0)
	v_mov_b32_e32 v23, v30
	v_mov_b32_e32 v25, v31
	v_mov_b32_e32 v11, v28
	v_mov_b32_e32 v13, v29
	v_pk_add_f32 v[14:15], v[22:23], v[24:25]
	v_pk_add_f32 v[10:11], v[10:11], v[12:13]
	s_nop 0
	v_pk_add_f32 v[10:11], v[10:11], v[14:15]
	s_nop 0
	v_add_f32_e32 v4, v10, v11
	v_fmamk_f32 v4, v4, 0x3a800000, v19
	v_mul_f32_e32 v10, 0x4b800000, v4
	v_cmp_gt_f32_e32 vcc, s13, v4
	s_nop 1
	v_cndmask_b32_e32 v4, v4, v10, vcc
	v_rsq_f32_e32 v10, v4
	v_or_b32_e32 v4, s0, v17
	v_lshlrev_b32_e32 v4, 1, v4
	v_lshl_add_u64 v[8:9], v[8:9], 0, v[4:5]
	v_mul_f32_e32 v4, 0x45800000, v10
	v_cndmask_b32_e32 v4, v10, v4, vcc
	v_mul_f32_e32 v4, 0x3d800000, v4
	v_pk_mul_f32 v[0:1], v[0:1], v[4:5] op_sel_hi:[1,0]
	v_pk_mul_f32 v[2:3], v[2:3], v[4:5] op_sel_hi:[1,0]
	v_cvt_pk_bf16_f32 v0, v0, v1
	v_cvt_pk_bf16_f32 v1, v2, v3
	global_store_dwordx2 v[8:9], v[0:1], off
	s_cbranch_scc0 .LBB0_999

; template <int MODE>
; __device__ __forceinline__ void sgemm_sample(LAS unsigned char* lds, const bf16_t* A, const bf16_t* Bt, int K, const float* resid, float* out, bf16_t* xb, float* ssq_out, const float* ssq_in) {
;     ...
;     for (int uu = u; uu < 2048; uu += gridDim.x * 8) {
;         const int rt = uu >> 6, ct = uu & 63; const int row = NTOKP + rt * 16 + fr, col0 = ct * 16 + fq * 4;
;         const bf16_t* ap = A + (size_t)row * K + fq * 8; const bf16_t* bp = Bt + (size_t)(ct * 16 + fr) * K + fq * 8;
;         f32x4 acc = {0.f, 0.f, 0.f, 0.f};
; #pragma unroll 8
;         for (int ks = 0; ks < K / 32; ++ks) {
;             const bf16x8 a = *(const bf16x8*)(ap + ks * 32); const bf16x8 b = *(const bf16x8*)(bp + ks * 32);
;             acc = __builtin_amdgcn_mfma_f32_16x16x32_bf16(b, a, acc, 0, 0, 0);
;         }
;         if (MODE == 0) {
;             const f32x4 x = *(const f32x4*)(resid + (size_t)(row - NTOKP) * D + col0) + acc;
.LBB0_1168:
	s_and_b32 s6, s15, 63
	v_lshl_or_b32 v4, s6, 15, v21
	s_ashr_i32 s6, s3, 2
	s_and_b32 s6, s6, -16
	s_add_i32 s6, s6, 0x8000
	v_or_b32_e32 v12, s6, v17
	v_ashrrev_i32_e32 v13, 31, v12
	v_lshlrev_b64 v[8:9], 11, v[12:13]
	v_lshl_add_u64 v[10:11], v[6:7], 0, v[4:5]
	v_lshl_add_u64 v[14:15], v[6:7], 0, v[8:9]
	s_mov_b64 s[18:19], 0
	v_mov_b32_e32 v0, 0
	v_mov_b32_e32 v1, v5
	v_mov_b32_e32 v2, v5
	v_mov_b32_e32 v3, v5
	s_cmpk_lg_i32 s34, 0x100
	s_cbranch_scc1 .LBB0_1169
	s_waitcnt vmcnt(0)
	s_and_b32 s20, s3, 63
	v_lshl_or_b32 v24, s20, 4, v18
	v_lshlrev_b64 v[14:15], 12, v[12:13]
	v_lshl_add_u64 v[10:11], s[10:11], 0, v[14:15]
	v_lshlrev_b32_e32 v4, 2, v24
	v_lshl_add_u64 v[10:11], v[10:11], 0, v[4:5]
	v_add_co_u32_e32 v10, vcc, 0xf8000000, v10
	v_lshl_add_u64 v[14:15], s[90:91], 0, v[14:15]
	s_nop 0
	v_addc_co_u32_e32 v11, vcc, -1, v11, vcc
	global_load_dwordx4 v[10:13], v[10:11], off
	s_lshr_b32 s100, s2, 3
	s_lshl_b32 s100, s100, 4
	s_add_i32 s100, s100, 0x8000
	s_mul_i32 s100, s100, 0x800
	s_add_u32 s96, s92, s100
	s_addc_u32 s97, s93, 0
	s_add_u32 s96, s96, 0x15780000
	s_addc_u32 s97, s97, 0
	s_and_b32 s100, s2, 7
	s_lshl_b32 s100, s100, 7
	s_mul_i32 s100, s100, 0x800
	s_add_u32 s98, s92, s100
	s_addc_u32 s99, s93, 0
	s_add_u32 s98, s98, 0x1040000
	s_addc_u32 s99, s99, 0
	v_lshrrev_b32_e32 v192, 4, v200
	v_and_b32_e32 v193, 15, v200
	v_and_b32_e32 v194, 15, v192
	v_xor_b32_e32 v193, v193, v194
	v_lshlrev_b32_e32 v193, 4, v193
	s_mov_b32 s100, 0x800
	v_mad_u32_u24 v144, v192, s100, v193
	v_add_u32_e32 v145, 0x10000, v144
	v_add_u32_e32 v146, 0x20000, v144
	v_add_u32_e32 v147, 0x30000, v144
	v_mad_u32_u24 v148, v194, s100, v193
	v_lshlrev_b32_e32 v149, 4, v200
	v_add_u32_e32 v149, 1024, v149
	v_and_b32_e32 v150, 0xff, v200
	v_lshlrev_b32_e32 v150, 4, v150
	v_add_u32_e32 v150, 33792, v150
	v_and_b32_e32 v192, 15, v200
	v_bfe_u32 v193, v200, 4, 2
	v_and_b32_e32 v194, 3, v192
	v_xor_b32_e32 v193, v193, v194
	v_lshlrev_b32_e32 v193, 4, v193
	v_lshrrev_b32_e32 v194, 2, v192
	v_lshl_add_u32 v193, v194, 6, v193
	v_lshl_add_u32 v193, v192, 8, v193
	v_add_u32_e32 v151, 33792, v193
	v_lshrrev_b32_e32 v194, 6, v200
	v_lshlrev_b32_e32 v194, 12, v194
	v_add_u32_e32 v155, v193, v194
	v_add_u32_e32 v155, 1024, v155
	v_xor_b32_e32 v152, 0x40, v151
	v_xor_b32_e32 v156, 0x40, v155
	v_xor_b32_e32 v153, 0x80, v151
	v_xor_b32_e32 v157, 0x80, v155
	v_xor_b32_e32 v154, 0xc0, v151
	v_xor_b32_e32 v158, 0xc0, v155
	global_load_dwordx4 v[64:67], v144, s[98:99]
	global_load_dwordx4 v[68:71], v145, s[98:99]
	global_load_dwordx4 v[72:75], v146, s[98:99]
	global_load_dwordx4 v[76:79], v147, s[98:99]
	global_load_dwordx4 v[80:83], v148, s[96:97]
	s_add_u32 s98, s98, 0x100
	s_addc_u32 s99, s99, 0
	s_add_u32 s96, s96, 0x100
	s_addc_u32 s97, s97, 0
	global_load_dwordx4 v[84:87], v144, s[98:99]
	global_load_dwordx4 v[88:91], v145, s[98:99]
	global_load_dwordx4 v[92:95], v146, s[98:99]
	global_load_dwordx4 v[96:99], v147, s[98:99]
	global_load_dwordx4 v[100:103], v148, s[96:97]
	s_add_u32 s98, s98, 0x100
	s_addc_u32 s99, s99, 0
	s_add_u32 s96, s96, 0x100
	s_addc_u32 s97, s97, 0
	global_load_dwordx4 v[104:107], v144, s[98:99]
	global_load_dwordx4 v[108:111], v145, s[98:99]
	global_load_dwordx4 v[112:115], v146, s[98:99]
	global_load_dwordx4 v[116:119], v147, s[98:99]
	global_load_dwordx4 v[120:123], v148, s[96:97]
	s_add_u32 s98, s98, 0x100
	s_addc_u32 s99, s99, 0
	s_add_u32 s96, s96, 0x100
	s_addc_u32 s97, s97, 0
	global_load_dwordx4 v[124:127], v144, s[98:99]
	global_load_dwordx4 v[128:131], v145, s[98:99]
	global_load_dwordx4 v[132:135], v146, s[98:99]
	global_load_dwordx4 v[136:139], v147, s[98:99]
	global_load_dwordx4 v[140:143], v148, s[96:97]
	s_add_u32 s98, s98, 0x100
	s_addc_u32 s99, s99, 0
	s_add_u32 s96, s96, 0x100
	s_addc_u32 s97, s97, 0
	s_waitcnt vmcnt(19)
	ds_write_b128 v149, v[64:67]
	s_waitcnt vmcnt(18)
	ds_write_b128 v149, v[68:71] offset:8192
	s_waitcnt vmcnt(17)
	ds_write_b128 v149, v[72:75] offset:16384
	s_waitcnt vmcnt(16)
	ds_write_b128 v149, v[76:79] offset:24576
	s_waitcnt vmcnt(15)
	ds_write_b128 v150, v[80:83]
	s_waitcnt lgkmcnt(0)
	s_barrier
	s_waitcnt vmcnt(14)
	ds_write_b128 v149, v[84:87] offset:36864
	s_waitcnt vmcnt(13)
	ds_write_b128 v149, v[88:91] offset:45056
	s_waitcnt vmcnt(12)
	ds_write_b128 v149, v[92:95] offset:53248
	s_waitcnt vmcnt(11)
	ds_write_b128 v149, v[96:99] offset:61440
	s_waitcnt vmcnt(10)
	ds_write_b128 v150, v[100:103] offset:36864
	global_load_dwordx4 v[64:67], v144, s[98:99]
	global_load_dwordx4 v[68:71], v145, s[98:99]
	global_load_dwordx4 v[72:75], v146, s[98:99]
	global_load_dwordx4 v[76:79], v147, s[98:99]
	global_load_dwordx4 v[80:83], v148, s[96:97]
	s_add_u32 s98, s98, 0x100
	s_addc_u32 s99, s99, 0
	s_add_u32 s96, s96, 0x100
	s_addc_u32 s97, s97, 0
	ds_read_b128 v[160:163], v155
	ds_read_b128 v[164:167], v151
	ds_read_b128 v[168:171], v156
	ds_read_b128 v[172:175], v152
	ds_read_b128 v[176:179], v157
	ds_read_b128 v[180:183], v153
	ds_read_b128 v[184:187], v158
	ds_read_b128 v[188:191], v154
	s_waitcnt lgkmcnt(6)
	v_mfma_f32_16x16x32_bf16 v[0:3], v[160:163], v[164:167], v[0:3]
	s_waitcnt lgkmcnt(4)
	v_mfma_f32_16x16x32_bf16 v[0:3], v[168:171], v[172:175], v[0:3]
	s_waitcnt lgkmcnt(2)
	v_mfma_f32_16x16x32_bf16 v[0:3], v[176:179], v[180:183], v[0:3]
	s_waitcnt lgkmcnt(0)
	v_mfma_f32_16x16x32_bf16 v[0:3], v[184:187], v[188:191], v[0:3]
	s_waitcnt lgkmcnt(0)
	s_barrier
; template <int MODE>
; __device__ __forceinline__ void sgemm_sample(LAS unsigned char* lds, const bf16_t* A, const bf16_t* Bt, int K, const float* resid, float* out, bf16_t* xb, float* ssq_out, const float* ssq_in) {
;     ...
; #pragma unroll 8
;         for (int ks = 0; ks < K / 32; ++ks) {
;             const bf16x8 a = *(const bf16x8*)(ap + ks * 32); const bf16x8 b = *(const bf16x8*)(bp + ks * 32);
;             acc = __builtin_amdgcn_mfma_f32_16x16x32_bf16(b, a, acc, 0, 0, 0);
;         }
	s_waitcnt vmcnt(14)
	ds_write_b128 v149, v[104:107]
	s_waitcnt vmcnt(13)
	ds_write_b128 v149, v[108:111] offset:8192
	s_waitcnt vmcnt(12)
	ds_write_b128 v149, v[112:115] offset:16384
	s_waitcnt vmcnt(11)
	ds_write_b128 v149, v[116:119] offset:24576
	s_waitcnt vmcnt(10)
	ds_write_b128 v150, v[120:123]
	global_load_dwordx4 v[84:87], v144, s[98:99]
	global_load_dwordx4 v[88:91], v145, s[98:99]
	global_load_dwordx4 v[92:95], v146, s[98:99]
	global_load_dwordx4 v[96:99], v147, s[98:99]
	global_load_dwordx4 v[100:103], v148, s[96:97]
	s_add_u32 s98, s98, 0x100
	s_addc_u32 s99, s99, 0
	s_add_u32 s96, s96, 0x100
	s_addc_u32 s97, s97, 0
	ds_read_b128 v[160:163], v155 offset:36864
	ds_read_b128 v[164:167], v151 offset:36864
	ds_read_b128 v[168:171], v156 offset:36864
	ds_read_b128 v[172:175], v152 offset:36864
	ds_read_b128 v[176:179], v157 offset:36864
	ds_read_b128 v[180:183], v153 offset:36864
	ds_read_b128 v[184:187], v158 offset:36864
	ds_read_b128 v[188:191], v154 offset:36864
	s_waitcnt lgkmcnt(6)
	v_mfma_f32_16x16x32_bf16 v[0:3], v[160:163], v[164:167], v[0:3]
	s_waitcnt lgkmcnt(4)
	v_mfma_f32_16x16x32_bf16 v[0:3], v[168:171], v[172:175], v[0:3]
	s_waitcnt lgkmcnt(2)
	v_mfma_f32_16x16x32_bf16 v[0:3], v[176:179], v[180:183], v[0:3]
	s_waitcnt lgkmcnt(0)
	v_mfma_f32_16x16x32_bf16 v[0:3], v[184:187], v[188:191], v[0:3]
	s_waitcnt lgkmcnt(0)
	s_barrier
	s_waitcnt vmcnt(14)
	ds_write_b128 v149, v[124:127] offset:36864
	s_waitcnt vmcnt(13)
	ds_write_b128 v149, v[128:131] offset:45056
	s_waitcnt vmcnt(12)
	ds_write_b128 v149, v[132:135] offset:53248
	s_waitcnt vmcnt(11)
	ds_write_b128 v149, v[136:139] offset:61440
	s_waitcnt vmcnt(10)
	ds_write_b128 v150, v[140:143] offset:36864
	global_load_dwordx4 v[104:107], v144, s[98:99]
	global_load_dwordx4 v[108:111], v145, s[98:99]
	global_load_dwordx4 v[112:115], v146, s[98:99]
	global_load_dwordx4 v[116:119], v147, s[98:99]
	global_load_dwordx4 v[120:123], v148, s[96:97]
	s_add_u32 s98, s98, 0x100
	s_addc_u32 s99, s99, 0
	s_add_u32 s96, s96, 0x100
	s_addc_u32 s97, s97, 0
	ds_read_b128 v[160:163], v155
	ds_read_b128 v[164:167], v151
	ds_read_b128 v[168:171], v156
	ds_read_b128 v[172:175], v152
	ds_read_b128 v[176:179], v157
	ds_read_b128 v[180:183], v153
	ds_read_b128 v[184:187], v158
	ds_read_b128 v[188:191], v154
	s_waitcnt lgkmcnt(6)
	v_mfma_f32_16x16x32_bf16 v[0:3], v[160:163], v[164:167], v[0:3]
	s_waitcnt lgkmcnt(4)
	v_mfma_f32_16x16x32_bf16 v[0:3], v[168:171], v[172:175], v[0:3]
	s_waitcnt lgkmcnt(2)
	v_mfma_f32_16x16x32_bf16 v[0:3], v[176:179], v[180:183], v[0:3]
	s_waitcnt lgkmcnt(0)
	v_mfma_f32_16x16x32_bf16 v[0:3], v[184:187], v[188:191], v[0:3]
	s_waitcnt lgkmcnt(0)
	s_barrier
	s_waitcnt vmcnt(14)
	ds_write_b128 v149, v[64:67]
	s_waitcnt vmcnt(13)
	ds_write_b128 v149, v[68:71] offset:8192
	s_waitcnt vmcnt(12)
	ds_write_b128 v149, v[72:75] offset:16384
	s_waitcnt vmcnt(11)
	ds_write_b128 v149, v[76:79] offset:24576
	s_waitcnt vmcnt(10)
	ds_write_b128 v150, v[80:83]
	global_load_dwordx4 v[124:127], v144, s[98:99]
	global_load_dwordx4 v[128:131], v145, s[98:99]
	global_load_dwordx4 v[132:135], v146, s[98:99]
	global_load_dwordx4 v[136:139], v147, s[98:99]
	global_load_dwordx4 v[140:143], v148, s[96:97]
	s_add_u32 s98, s98, 0x100
	s_addc_u32 s99, s99, 0
	s_add_u32 s96, s96, 0x100
	s_addc_u32 s97, s97, 0
	ds_read_b128 v[160:163], v155 offset:36864
	ds_read_b128 v[164:167], v151 offset:36864
	ds_read_b128 v[168:171], v156 offset:36864
	ds_read_b128 v[172:175], v152 offset:36864
	ds_read_b128 v[176:179], v157 offset:36864
	ds_read_b128 v[180:183], v153 offset:36864
	ds_read_b128 v[184:187], v158 offset:36864
	ds_read_b128 v[188:191], v154 offset:36864
	s_waitcnt lgkmcnt(6)
	v_mfma_f32_16x16x32_bf16 v[0:3], v[160:163], v[164:167], v[0:3]
	s_waitcnt lgkmcnt(4)
	v_mfma_f32_16x16x32_bf16 v[0:3], v[168:171], v[172:175], v[0:3]
	s_waitcnt lgkmcnt(2)
	v_mfma_f32_16x16x32_bf16 v[0:3], v[176:179], v[180:183], v[0:3]
	s_waitcnt lgkmcnt(0)
	v_mfma_f32_16x16x32_bf16 v[0:3], v[184:187], v[188:191], v[0:3]
	s_waitcnt lgkmcnt(0)
	s_barrier
	s_waitcnt vmcnt(14)
	ds_write_b128 v149, v[84:87] offset:36864
	s_waitcnt vmcnt(13)
	ds_write_b128 v149, v[88:91] offset:45056
	s_waitcnt vmcnt(12)
	ds_write_b128 v149, v[92:95] offset:53248
	s_waitcnt vmcnt(11)
	ds_write_b128 v149, v[96:99] offset:61440
	s_waitcnt vmcnt(10)
	ds_write_b128 v150, v[100:103] offset:36864
	ds_read_b128 v[160:163], v155
	ds_read_b128 v[164:167], v151
	ds_read_b128 v[168:171], v156
	ds_read_b128 v[172:175], v152
	ds_read_b128 v[176:179], v157
	ds_read_b128 v[180:183], v153
	ds_read_b128 v[184:187], v158
	ds_read_b128 v[188:191], v154
	s_waitcnt lgkmcnt(6)
	v_mfma_f32_16x16x32_bf16 v[0:3], v[160:163], v[164:167], v[0:3]
	s_waitcnt lgkmcnt(4)
	v_mfma_f32_16x16x32_bf16 v[0:3], v[168:171], v[172:175], v[0:3]
	s_waitcnt lgkmcnt(2)
	v_mfma_f32_16x16x32_bf16 v[0:3], v[176:179], v[180:183], v[0:3]
	s_waitcnt lgkmcnt(0)
	v_mfma_f32_16x16x32_bf16 v[0:3], v[184:187], v[188:191], v[0:3]
	s_waitcnt lgkmcnt(0)
	s_barrier
; #define LAS __attribute__((address_space(3)))
; __device__ __forceinline__ unsigned cvt_pk_bf16(float lo, float hi) { f32x2 f = {lo, hi}; bf16x2_t v = __builtin_convertvector(f, bf16x2_t); return __builtin_bit_cast(unsigned, v); }
; template <int MODE>
; __device__ __forceinline__ void sgemm_sample(LAS unsigned char* lds, const bf16_t* A, const bf16_t* Bt, int K, const float* resid, float* out, bf16_t* xb, float* ssq_out, const float* ssq_in) {
;     ...
; #pragma unroll 8
;         for (int ks = 0; ks < K / 32; ++ks) {
;             const bf16x8 a = *(const bf16x8*)(ap + ks * 32); const bf16x8 b = *(const bf16x8*)(bp + ks * 32);
;             acc = __builtin_amdgcn_mfma_f32_16x16x32_bf16(b, a, acc, 0, 0, 0);
;         }
;         if (MODE == 0) {
;             const f32x4 x = *(const f32x4*)(resid + (size_t)(row - NTOKP) * D + col0) + acc;
;             *(f32x4*)(out + (size_t)row * D + col0) = x;
;             if (xb) { u32x2 wv; wv.x = cvt_pk_bf16(x[0], x[1]); wv.y = cvt_pk_bf16(x[2], x[3]); *(u32x2*)(xb + (size_t)row * D + col0) = wv; }
;             if (ssq_out) {
;                 float ss = (x[0] * x[0] + x[1] * x[1]) + (x[2] * x[2] + x[3] * x[3]); ss += __shfl_xor(ss, 16); ss += __shfl_xor(ss, 32);
;                 if (fq == 0) *(LAS float*)(lds + (w * 16 + fr) * 4) = ss;
;                 __syncthreads();
	s_waitcnt vmcnt(9)
	ds_write_b128 v149, v[104:107]
	s_waitcnt vmcnt(8)
	ds_write_b128 v149, v[108:111] offset:8192
	s_waitcnt vmcnt(7)
	ds_write_b128 v149, v[112:115] offset:16384
	s_waitcnt vmcnt(6)
	ds_write_b128 v149, v[116:119] offset:24576
	s_waitcnt vmcnt(5)
	ds_write_b128 v150, v[120:123]
	ds_read_b128 v[160:163], v155 offset:36864
	ds_read_b128 v[164:167], v151 offset:36864
	ds_read_b128 v[168:171], v156 offset:36864
	ds_read_b128 v[172:175], v152 offset:36864
	ds_read_b128 v[176:179], v157 offset:36864
	ds_read_b128 v[180:183], v153 offset:36864
	ds_read_b128 v[184:187], v158 offset:36864
	ds_read_b128 v[188:191], v154 offset:36864
	s_waitcnt lgkmcnt(6)
	v_mfma_f32_16x16x32_bf16 v[0:3], v[160:163], v[164:167], v[0:3]
	s_waitcnt lgkmcnt(4)
	v_mfma_f32_16x16x32_bf16 v[0:3], v[168:171], v[172:175], v[0:3]
	s_waitcnt lgkmcnt(2)
	v_mfma_f32_16x16x32_bf16 v[0:3], v[176:179], v[180:183], v[0:3]
	s_waitcnt lgkmcnt(0)
	v_mfma_f32_16x16x32_bf16 v[0:3], v[184:187], v[188:191], v[0:3]
	s_waitcnt lgkmcnt(0)
	s_barrier
	s_waitcnt vmcnt(4)
	ds_write_b128 v149, v[124:127] offset:36864
	s_waitcnt vmcnt(3)
	ds_write_b128 v149, v[128:131] offset:45056
	s_waitcnt vmcnt(2)
	ds_write_b128 v149, v[132:135] offset:53248
	s_waitcnt vmcnt(1)
	ds_write_b128 v149, v[136:139] offset:61440
	s_waitcnt vmcnt(0)
	ds_write_b128 v150, v[140:143] offset:36864
	ds_read_b128 v[160:163], v155
	ds_read_b128 v[164:167], v151
	ds_read_b128 v[168:171], v156
	ds_read_b128 v[172:175], v152
	ds_read_b128 v[176:179], v157
	ds_read_b128 v[180:183], v153
	ds_read_b128 v[184:187], v158
	ds_read_b128 v[188:191], v154
	s_waitcnt lgkmcnt(6)
	v_mfma_f32_16x16x32_bf16 v[0:3], v[160:163], v[164:167], v[0:3]
	s_waitcnt lgkmcnt(4)
	v_mfma_f32_16x16x32_bf16 v[0:3], v[168:171], v[172:175], v[0:3]
	s_waitcnt lgkmcnt(2)
	v_mfma_f32_16x16x32_bf16 v[0:3], v[176:179], v[180:183], v[0:3]
	s_waitcnt lgkmcnt(0)
	v_mfma_f32_16x16x32_bf16 v[0:3], v[184:187], v[188:191], v[0:3]
	s_waitcnt lgkmcnt(0)
	s_barrier
	ds_read_b128 v[160:163], v155 offset:36864
	ds_read_b128 v[164:167], v151 offset:36864
	ds_read_b128 v[168:171], v156 offset:36864
	ds_read_b128 v[172:175], v152 offset:36864
	ds_read_b128 v[176:179], v157 offset:36864
	ds_read_b128 v[180:183], v153 offset:36864
	ds_read_b128 v[184:187], v158 offset:36864
	ds_read_b128 v[188:191], v154 offset:36864
	s_waitcnt lgkmcnt(6)
	v_mfma_f32_16x16x32_bf16 v[0:3], v[160:163], v[164:167], v[0:3]
	s_waitcnt lgkmcnt(4)
	v_mfma_f32_16x16x32_bf16 v[0:3], v[168:171], v[172:175], v[0:3]
	s_waitcnt lgkmcnt(2)
	v_mfma_f32_16x16x32_bf16 v[0:3], v[176:179], v[180:183], v[0:3]
	s_waitcnt lgkmcnt(0)
	v_mfma_f32_16x16x32_bf16 v[0:3], v[184:187], v[188:191], v[0:3]
	s_nop 7
	s_branch .Lsgx2_done
.LBB0_1169:
	v_lshl_add_u64 v[24:25], v[14:15], 0, s[18:19]
	v_add_co_u32_e32 v60, vcc, 0x15780000, v24
	v_lshl_add_u64 v[26:27], v[10:11], 0, s[18:19]
	s_nop 0
	v_addc_co_u32_e32 v61, vcc, 0, v25, vcc
	v_add_co_u32_e32 v62, vcc, 0x1040000, v26
	s_add_u32 s18, s18, 0x200
	s_nop 0
	v_addc_co_u32_e32 v63, vcc, 0, v27, vcc
	global_load_dwordx4 v[24:27], v[60:61], off
	global_load_dwordx4 v[28:31], v[60:61], off offset:64
	global_load_dwordx4 v[32:35], v[60:61], off offset:128
	global_load_dwordx4 v[36:39], v[60:61], off offset:192
	global_load_dwordx4 v[40:43], v[60:61], off offset:256
	global_load_dwordx4 v[44:47], v[62:63], off
	global_load_dwordx4 v[48:51], v[62:63], off offset:64
	global_load_dwordx4 v[52:55], v[62:63], off offset:128
	global_load_dwordx4 v[56:59], v[62:63], off offset:192
	s_addc_u32 s19, s19, 0
	s_cmpk_eq_i32 s18, 0x800
	s_waitcnt vmcnt(3)
	v_mfma_f32_16x16x32_bf16 v[0:3], v[44:47], v[24:27], v[0:3]
	global_load_dwordx4 v[24:27], v[62:63], off offset:256
	s_waitcnt vmcnt(3)
	v_mfma_f32_16x16x32_bf16 v[0:3], v[48:51], v[28:31], v[0:3]
	global_load_dwordx4 v[28:31], v[62:63], off offset:320
	s_waitcnt vmcnt(3)
	v_mfma_f32_16x16x32_bf16 v[0:3], v[52:55], v[32:35], v[0:3]
	global_load_dwordx4 v[32:35], v[60:61], off offset:320
	s_waitcnt vmcnt(3)
	v_mfma_f32_16x16x32_bf16 v[0:3], v[56:59], v[36:39], v[0:3]
	global_load_dwordx4 v[36:39], v[62:63], off offset:384
	global_load_dwordx4 v[44:47], v[60:61], off offset:384
	s_waitcnt vmcnt(4)
	v_mfma_f32_16x16x32_bf16 v[0:3], v[24:27], v[40:43], v[0:3]
	global_load_dwordx4 v[24:27], v[62:63], off offset:448
	s_waitcnt vmcnt(3)
	v_mfma_f32_16x16x32_bf16 v[0:3], v[28:31], v[32:35], v[0:3]
	global_load_dwordx4 v[28:31], v[60:61], off offset:448
	s_waitcnt vmcnt(2)
	v_mfma_f32_16x16x32_bf16 v[0:3], v[36:39], v[44:47], v[0:3]
	s_waitcnt vmcnt(0)
	v_mfma_f32_16x16x32_bf16 v[0:3], v[24:27], v[28:31], v[0:3]
	s_cbranch_scc0 .LBB0_1169
	s_and_b32 s20, s3, 63
	v_lshl_or_b32 v24, s20, 4, v18
	v_lshlrev_b64 v[14:15], 12, v[12:13]
	v_lshl_add_u64 v[10:11], s[10:11], 0, v[14:15]
	v_lshlrev_b32_e32 v4, 2, v24
	v_lshl_add_u64 v[10:11], v[10:11], 0, v[4:5]
	v_add_co_u32_e32 v10, vcc, 0xf8000000, v10
	v_lshl_add_u64 v[14:15], s[90:91], 0, v[14:15]
	s_nop 0
	v_addc_co_u32_e32 v11, vcc, -1, v11, vcc
	global_load_dwordx4 v[10:13], v[10:11], off
.Lsgx2_done:
	s_waitcnt vmcnt(0)
	v_pk_add_f32 v[2:3], v[2:3], v[12:13]
	v_pk_add_f32 v[0:1], v[0:1], v[10:11]
	v_mul_f32_e32 v11, v3, v3
	v_mul_f32_e32 v10, v1, v1
	v_fmac_f32_e32 v10, v0, v0
	v_fmac_f32_e32 v11, v2, v2
	v_add_f32_e32 v12, v10, v11
	ds_bpermute_b32 v13, v19, v12
	v_lshl_add_u64 v[10:11], v[14:15], 0, v[4:5]
	global_store_dwordx4 v[10:11], v[0:3], off
	v_cvt_pk_bf16_f32 v10, v0, v1
	v_cvt_pk_bf16_f32 v11, v2, v3
	s_waitcnt lgkmcnt(0)
	v_add_f32_e32 v0, v12, v13
	ds_bpermute_b32 v1, v20, v0
	v_lshl_add_u64 v[2:3], s[12:13], 0, v[8:9]
	v_lshlrev_b32_e32 v4, 1, v24
	v_lshl_add_u64 v[2:3], v[2:3], 0, v[4:5]
	global_store_dwordx2 v[2:3], v[10:11], off
	s_and_saveexec_b64 s[18:19], s[0:1]
	s_cbranch_execz .LBB0_1172
	s_waitcnt lgkmcnt(0)
	v_add_f32_e32 v0, v0, v1
	ds_write_b32 v22, v0

; template <int MODE>
; __device__ __forceinline__ void sgemm_sample(LAS unsigned char* lds, const bf16_t* A, const bf16_t* Bt, int K, const float* resid, float* out, bf16_t* xb, float* ssq_out, const float* ssq_in) {
;     ...
;     for (int uu = u; uu < 2048; uu += gridDim.x * 8) {
;         const int rt = uu >> 6, ct = uu & 63; const int row = NTOKP + rt * 16 + fr, col0 = ct * 16 + fq * 4;
;         const bf16_t* ap = A + (size_t)row * K + fq * 8; const bf16_t* bp = Bt + (size_t)(ct * 16 + fr) * K + fq * 8;
;         f32x4 acc = {0.f, 0.f, 0.f, 0.f};
; #pragma unroll 8
;         for (int ks = 0; ks < K / 32; ++ks) {
;             const bf16x8 a = *(const bf16x8*)(ap + ks * 32); const bf16x8 b = *(const bf16x8*)(bp + ks * 32);
;             acc = __builtin_amdgcn_mfma_f32_16x16x32_bf16(b, a, acc, 0, 0, 0);
;         }
;         if (MODE == 0) {
;             const f32x4 x = *(const f32x4*)(resid + (size_t)(row - NTOKP) * D + col0) + acc;
.LBB0_1348:
	s_ashr_i32 s0, s3, 2
	s_and_b32 s0, s0, -16
	v_add_u32_e32 v8, s0, v16
	s_lshl_b32 s0, s3, 4
	s_and_b32 s10, s0, 0x3f0
	v_or_b32_e32 v0, s10, v14
	v_mul_u32_u24_e32 v0, 0xb00, v0
	v_mad_i64_i32 v[10:11], s[0:1], v8, s5, v[6:7]
	v_lshlrev_b32_e32 v4, 1, v0
	v_ashrrev_i32_e32 v9, 31, v8
	v_lshl_add_u64 v[12:13], v[6:7], 0, v[4:5]
	s_mov_b64 s[0:1], 0
	v_mov_b32_e32 v0, 0
	s_waitcnt lgkmcnt(0)
	v_mov_b32_e32 v1, v5
	v_mov_b32_e32 v2, v5
	v_mov_b32_e32 v3, v5
	s_cmpk_lg_i32 s34, 0x100
	s_cbranch_scc1 .LBB0_1349
	s_waitcnt vmcnt(0)
	v_or_b32_e32 v4, s10, v15
	v_lshlrev_b64 v[12:13], 12, v[8:9]
	v_lshl_add_u64 v[8:9], s[8:9], 0, v[12:13]
	v_lshlrev_b32_e32 v4, 2, v4
	v_lshl_add_u64 v[8:9], v[8:9], 0, v[4:5]
	v_add_co_u32_e32 v8, vcc, 0xf8000000, v8
	s_add_i32 s3, s3, s4
	s_nop 0
	v_addc_co_u32_e32 v9, vcc, -1, v9, vcc
	global_load_dwordx4 v[8:11], v[8:9], off
	s_lshr_b32 s100, s2, 3
	s_lshl_b32 s100, s100, 4
	s_add_i32 s100, s100, 0x8000
	s_mul_i32 s100, s100, 0x1600
	s_add_u32 s96, s92, s100
	s_addc_u32 s97, s93, 0
	s_add_u32 s96, s96, 0x22c0000
	s_addc_u32 s97, s97, 0
	s_and_b32 s100, s2, 7
	s_lshl_b32 s100, s100, 7
	s_mul_i32 s100, s100, 0x1600
	s_add_u32 s98, s92, s100
	s_addc_u32 s99, s93, 0
	s_add_u32 s98, s98, 0x1d40000
	s_addc_u32 s99, s99, 0
	v_lshrrev_b32_e32 v192, 4, v200
	v_and_b32_e32 v193, 15, v200
	v_and_b32_e32 v194, 15, v192
	v_xor_b32_e32 v193, v193, v194
	v_lshlrev_b32_e32 v193, 4, v193
	s_mov_b32 s100, 0x1600
	v_mad_u32_u24 v144, v192, s100, v193
	v_add_u32_e32 v145, 0x2c000, v144
	v_add_u32_e32 v146, 0x58000, v144
	v_add_u32_e32 v147, 0x84000, v144
	v_mad_u32_u24 v148, v194, s100, v193
	v_lshlrev_b32_e32 v149, 4, v200
	v_add_u32_e32 v149, 1024, v149
	v_and_b32_e32 v150, 0xff, v200
	v_lshlrev_b32_e32 v150, 4, v150
	v_add_u32_e32 v150, 33792, v150
	v_and_b32_e32 v192, 15, v200
	v_bfe_u32 v193, v200, 4, 2
	v_and_b32_e32 v194, 3, v192
	v_xor_b32_e32 v193, v193, v194
	v_lshlrev_b32_e32 v193, 4, v193
	v_lshrrev_b32_e32 v194, 2, v192
	v_lshl_add_u32 v193, v194, 6, v193
	v_lshl_add_u32 v193, v192, 8, v193
	v_add_u32_e32 v151, 33792, v193
	v_lshrrev_b32_e32 v194, 6, v200
	v_lshlrev_b32_e32 v194, 12, v194
	v_add_u32_e32 v155, v193, v194
	v_add_u32_e32 v155, 1024, v155
	v_xor_b32_e32 v152, 0x40, v151
	v_xor_b32_e32 v156, 0x40, v155
	v_xor_b32_e32 v153, 0x80, v151
	v_xor_b32_e32 v157, 0x80, v155
	v_xor_b32_e32 v154, 0xc0, v151
	v_xor_b32_e32 v158, 0xc0, v155
	global_load_dwordx4 v[64:67], v144, s[98:99]
	global_load_dwordx4 v[68:71], v145, s[98:99]
	global_load_dwordx4 v[72:75], v146, s[98:99]
	global_load_dwordx4 v[76:79], v147, s[98:99]
	global_load_dwordx4 v[80:83], v148, s[96:97]
	s_add_u32 s98, s98, 0x100
	s_addc_u32 s99, s99, 0
	s_add_u32 s96, s96, 0x100
	s_addc_u32 s97, s97, 0
	global_load_dwordx4 v[84:87], v144, s[98:99]
	global_load_dwordx4 v[88:91], v145, s[98:99]
	global_load_dwordx4 v[92:95], v146, s[98:99]
	global_load_dwordx4 v[96:99], v147, s[98:99]
	global_load_dwordx4 v[100:103], v148, s[96:97]
	s_add_u32 s98, s98, 0x100
	s_addc_u32 s99, s99, 0
	s_add_u32 s96, s96, 0x100
	s_addc_u32 s97, s97, 0
	global_load_dwordx4 v[104:107], v144, s[98:99]
	global_load_dwordx4 v[108:111], v145, s[98:99]
	global_load_dwordx4 v[112:115], v146, s[98:99]
	global_load_dwordx4 v[116:119], v147, s[98:99]
	global_load_dwordx4 v[120:123], v148, s[96:97]
	s_add_u32 s98, s98, 0x100
	s_addc_u32 s99, s99, 0
	s_add_u32 s96, s96, 0x100
	s_addc_u32 s97, s97, 0
	global_load_dwordx4 v[124:127], v144, s[98:99]
	global_load_dwordx4 v[128:131], v145, s[98:99]
	global_load_dwordx4 v[132:135], v146, s[98:99]
	global_load_dwordx4 v[136:139], v147, s[98:99]
	global_load_dwordx4 v[140:143], v148, s[96:97]
	s_add_u32 s98, s98, 0x100
	s_addc_u32 s99, s99, 0
	s_add_u32 s96, s96, 0x100
	s_addc_u32 s97, s97, 0
	s_waitcnt vmcnt(19)
	ds_write_b128 v149, v[64:67]
	s_waitcnt vmcnt(18)
	ds_write_b128 v149, v[68:71] offset:8192
	s_waitcnt vmcnt(17)
	ds_write_b128 v149, v[72:75] offset:16384
	s_waitcnt vmcnt(16)
	ds_write_b128 v149, v[76:79] offset:24576
	s_waitcnt vmcnt(15)
	ds_write_b128 v150, v[80:83]
	s_waitcnt lgkmcnt(0)
	s_barrier
	s_waitcnt vmcnt(14)
	ds_write_b128 v149, v[84:87] offset:36864
	s_waitcnt vmcnt(13)
	ds_write_b128 v149, v[88:91] offset:45056
	s_waitcnt vmcnt(12)
	ds_write_b128 v149, v[92:95] offset:53248
	s_waitcnt vmcnt(11)
	ds_write_b128 v149, v[96:99] offset:61440
	s_waitcnt vmcnt(10)
	ds_write_b128 v150, v[100:103] offset:36864
	global_load_dwordx4 v[64:67], v144, s[98:99]
	global_load_dwordx4 v[68:71], v145, s[98:99]
	global_load_dwordx4 v[72:75], v146, s[98:99]
	global_load_dwordx4 v[76:79], v147, s[98:99]
	global_load_dwordx4 v[80:83], v148, s[96:97]
	s_add_u32 s98, s98, 0x100
	s_addc_u32 s99, s99, 0
	s_add_u32 s96, s96, 0x100
	s_addc_u32 s97, s97, 0
	ds_read_b128 v[160:163], v155
	ds_read_b128 v[164:167], v151
	ds_read_b128 v[168:171], v156
	ds_read_b128 v[172:175], v152
	ds_read_b128 v[176:179], v157
	ds_read_b128 v[180:183], v153
	ds_read_b128 v[184:187], v158
	ds_read_b128 v[188:191], v154
	s_waitcnt lgkmcnt(6)
	v_mfma_f32_16x16x32_bf16 v[0:3], v[160:163], v[164:167], v[0:3]
	s_waitcnt lgkmcnt(4)
	v_mfma_f32_16x16x32_bf16 v[0:3], v[168:171], v[172:175], v[0:3]
	s_waitcnt lgkmcnt(2)
	v_mfma_f32_16x16x32_bf16 v[0:3], v[176:179], v[180:183], v[0:3]
	s_waitcnt lgkmcnt(0)
	v_mfma_f32_16x16x32_bf16 v[0:3], v[184:187], v[188:191], v[0:3]
	s_waitcnt lgkmcnt(0)
	s_barrier
; template <int MODE>
; __device__ __forceinline__ void sgemm_sample(LAS unsigned char* lds, const bf16_t* A, const bf16_t* Bt, int K, const float* resid, float* out, bf16_t* xb, float* ssq_out, const float* ssq_in) {
;     ...
; #pragma unroll 8
;         for (int ks = 0; ks < K / 32; ++ks) {
;             const bf16x8 a = *(const bf16x8*)(ap + ks * 32); const bf16x8 b = *(const bf16x8*)(bp + ks * 32);
;             acc = __builtin_amdgcn_mfma_f32_16x16x32_bf16(b, a, acc, 0, 0, 0);
;         }
	s_waitcnt vmcnt(14)
	ds_write_b128 v149, v[104:107]
	s_waitcnt vmcnt(13)
	ds_write_b128 v149, v[108:111] offset:8192
	s_waitcnt vmcnt(12)
	ds_write_b128 v149, v[112:115] offset:16384
	s_waitcnt vmcnt(11)
	ds_write_b128 v149, v[116:119] offset:24576
	s_waitcnt vmcnt(10)
	ds_write_b128 v150, v[120:123]
	global_load_dwordx4 v[84:87], v144, s[98:99]
	global_load_dwordx4 v[88:91], v145, s[98:99]
	global_load_dwordx4 v[92:95], v146, s[98:99]
	global_load_dwordx4 v[96:99], v147, s[98:99]
	global_load_dwordx4 v[100:103], v148, s[96:97]
	s_add_u32 s98, s98, 0x100
	s_addc_u32 s99, s99, 0
	s_add_u32 s96, s96, 0x100
	s_addc_u32 s97, s97, 0
	ds_read_b128 v[160:163], v155 offset:36864
	ds_read_b128 v[164:167], v151 offset:36864
	ds_read_b128 v[168:171], v156 offset:36864
	ds_read_b128 v[172:175], v152 offset:36864
	ds_read_b128 v[176:179], v157 offset:36864
	ds_read_b128 v[180:183], v153 offset:36864
	ds_read_b128 v[184:187], v158 offset:36864
	ds_read_b128 v[188:191], v154 offset:36864
	s_waitcnt lgkmcnt(6)
	v_mfma_f32_16x16x32_bf16 v[0:3], v[160:163], v[164:167], v[0:3]
	s_waitcnt lgkmcnt(4)
	v_mfma_f32_16x16x32_bf16 v[0:3], v[168:171], v[172:175], v[0:3]
	s_waitcnt lgkmcnt(2)
	v_mfma_f32_16x16x32_bf16 v[0:3], v[176:179], v[180:183], v[0:3]
	s_waitcnt lgkmcnt(0)
	v_mfma_f32_16x16x32_bf16 v[0:3], v[184:187], v[188:191], v[0:3]
	s_waitcnt lgkmcnt(0)
	s_barrier
	s_waitcnt vmcnt(14)
	ds_write_b128 v149, v[124:127] offset:36864
	s_waitcnt vmcnt(13)
	ds_write_b128 v149, v[128:131] offset:45056
	s_waitcnt vmcnt(12)
	ds_write_b128 v149, v[132:135] offset:53248
	s_waitcnt vmcnt(11)
	ds_write_b128 v149, v[136:139] offset:61440
	s_waitcnt vmcnt(10)
	ds_write_b128 v150, v[140:143] offset:36864
	global_load_dwordx4 v[104:107], v144, s[98:99]
	global_load_dwordx4 v[108:111], v145, s[98:99]
	global_load_dwordx4 v[112:115], v146, s[98:99]
	global_load_dwordx4 v[116:119], v147, s[98:99]
	global_load_dwordx4 v[120:123], v148, s[96:97]
	s_add_u32 s98, s98, 0x100
	s_addc_u32 s99, s99, 0
	s_add_u32 s96, s96, 0x100
	s_addc_u32 s97, s97, 0
	ds_read_b128 v[160:163], v155
	ds_read_b128 v[164:167], v151
	ds_read_b128 v[168:171], v156
	ds_read_b128 v[172:175], v152
	ds_read_b128 v[176:179], v157
	ds_read_b128 v[180:183], v153
	ds_read_b128 v[184:187], v158
	ds_read_b128 v[188:191], v154
	s_waitcnt lgkmcnt(6)
	v_mfma_f32_16x16x32_bf16 v[0:3], v[160:163], v[164:167], v[0:3]
	s_waitcnt lgkmcnt(4)
	v_mfma_f32_16x16x32_bf16 v[0:3], v[168:171], v[172:175], v[0:3]
	s_waitcnt lgkmcnt(2)
	v_mfma_f32_16x16x32_bf16 v[0:3], v[176:179], v[180:183], v[0:3]
	s_waitcnt lgkmcnt(0)
	v_mfma_f32_16x16x32_bf16 v[0:3], v[184:187], v[188:191], v[0:3]
	s_waitcnt lgkmcnt(0)
	s_barrier
	s_waitcnt vmcnt(14)
	ds_write_b128 v149, v[64:67]
	s_waitcnt vmcnt(13)
	ds_write_b128 v149, v[68:71] offset:8192
	s_waitcnt vmcnt(12)
	ds_write_b128 v149, v[72:75] offset:16384
	s_waitcnt vmcnt(11)
	ds_write_b128 v149, v[76:79] offset:24576
	s_waitcnt vmcnt(10)
	ds_write_b128 v150, v[80:83]
	global_load_dwordx4 v[124:127], v144, s[98:99]
	global_load_dwordx4 v[128:131], v145, s[98:99]
	global_load_dwordx4 v[132:135], v146, s[98:99]
	global_load_dwordx4 v[136:139], v147, s[98:99]
	global_load_dwordx4 v[140:143], v148, s[96:97]
	s_add_u32 s98, s98, 0x100
	s_addc_u32 s99, s99, 0
	s_add_u32 s96, s96, 0x100
	s_addc_u32 s97, s97, 0
	ds_read_b128 v[160:163], v155 offset:36864
	ds_read_b128 v[164:167], v151 offset:36864
	ds_read_b128 v[168:171], v156 offset:36864
	ds_read_b128 v[172:175], v152 offset:36864
	ds_read_b128 v[176:179], v157 offset:36864
	ds_read_b128 v[180:183], v153 offset:36864
	ds_read_b128 v[184:187], v158 offset:36864
	ds_read_b128 v[188:191], v154 offset:36864
	s_waitcnt lgkmcnt(6)
	v_mfma_f32_16x16x32_bf16 v[0:3], v[160:163], v[164:167], v[0:3]
	s_waitcnt lgkmcnt(4)
	v_mfma_f32_16x16x32_bf16 v[0:3], v[168:171], v[172:175], v[0:3]
	s_waitcnt lgkmcnt(2)
	v_mfma_f32_16x16x32_bf16 v[0:3], v[176:179], v[180:183], v[0:3]
	s_waitcnt lgkmcnt(0)
	v_mfma_f32_16x16x32_bf16 v[0:3], v[184:187], v[188:191], v[0:3]
	s_waitcnt lgkmcnt(0)
	s_barrier
	s_waitcnt vmcnt(14)
	ds_write_b128 v149, v[84:87] offset:36864
	s_waitcnt vmcnt(13)
	ds_write_b128 v149, v[88:91] offset:45056
	s_waitcnt vmcnt(12)
	ds_write_b128 v149, v[92:95] offset:53248
	s_waitcnt vmcnt(11)
	ds_write_b128 v149, v[96:99] offset:61440
	s_waitcnt vmcnt(10)
	ds_write_b128 v150, v[100:103] offset:36864
	global_load_dwordx4 v[64:67], v144, s[98:99]
	global_load_dwordx4 v[68:71], v145, s[98:99]
	global_load_dwordx4 v[72:75], v146, s[98:99]
	global_load_dwordx4 v[76:79], v147, s[98:99]
	global_load_dwordx4 v[80:83], v148, s[96:97]
	s_add_u32 s98, s98, 0x100
	s_addc_u32 s99, s99, 0
	s_add_u32 s96, s96, 0x100
	s_addc_u32 s97, s97, 0
	ds_read_b128 v[160:163], v155
	ds_read_b128 v[164:167], v151
	ds_read_b128 v[168:171], v156
	ds_read_b128 v[172:175], v152
	ds_read_b128 v[176:179], v157
	ds_read_b128 v[180:183], v153
	ds_read_b128 v[184:187], v158
	ds_read_b128 v[188:191], v154
	s_waitcnt lgkmcnt(6)
	v_mfma_f32_16x16x32_bf16 v[0:3], v[160:163], v[164:167], v[0:3]
	s_waitcnt lgkmcnt(4)
	v_mfma_f32_16x16x32_bf16 v[0:3], v[168:171], v[172:175], v[0:3]
	s_waitcnt lgkmcnt(2)
	v_mfma_f32_16x16x32_bf16 v[0:3], v[176:179], v[180:183], v[0:3]
	s_waitcnt lgkmcnt(0)
	v_mfma_f32_16x16x32_bf16 v[0:3], v[184:187], v[188:191], v[0:3]
	s_waitcnt lgkmcnt(0)
	s_barrier
; template <int MODE>
; __device__ __forceinline__ void sgemm_sample(LAS unsigned char* lds, const bf16_t* A, const bf16_t* Bt, int K, const float* resid, float* out, bf16_t* xb, float* ssq_out, const float* ssq_in) {
;     ...
; #pragma unroll 8
;         for (int ks = 0; ks < K / 32; ++ks) {
;             const bf16x8 a = *(const bf16x8*)(ap + ks * 32); const bf16x8 b = *(const bf16x8*)(bp + ks * 32);
;             acc = __builtin_amdgcn_mfma_f32_16x16x32_bf16(b, a, acc, 0, 0, 0);
;         }
	s_waitcnt vmcnt(14)
	ds_write_b128 v149, v[104:107]
	s_waitcnt vmcnt(13)
	ds_write_b128 v149, v[108:111] offset:8192
	s_waitcnt vmcnt(12)
	ds_write_b128 v149, v[112:115] offset:16384
	s_waitcnt vmcnt(11)
	ds_write_b128 v149, v[116:119] offset:24576
	s_waitcnt vmcnt(10)
	ds_write_b128 v150, v[120:123]
	global_load_dwordx4 v[84:87], v144, s[98:99]
	global_load_dwordx4 v[88:91], v145, s[98:99]
	global_load_dwordx4 v[92:95], v146, s[98:99]
	global_load_dwordx4 v[96:99], v147, s[98:99]
	global_load_dwordx4 v[100:103], v148, s[96:97]
	s_add_u32 s98, s98, 0x100
	s_addc_u32 s99, s99, 0
	s_add_u32 s96, s96, 0x100
	s_addc_u32 s97, s97, 0
	ds_read_b128 v[160:163], v155 offset:36864
	ds_read_b128 v[164:167], v151 offset:36864
	ds_read_b128 v[168:171], v156 offset:36864
	ds_read_b128 v[172:175], v152 offset:36864
	ds_read_b128 v[176:179], v157 offset:36864
	ds_read_b128 v[180:183], v153 offset:36864
	ds_read_b128 v[184:187], v158 offset:36864
	ds_read_b128 v[188:191], v154 offset:36864
	s_waitcnt lgkmcnt(6)
	v_mfma_f32_16x16x32_bf16 v[0:3], v[160:163], v[164:167], v[0:3]
	s_waitcnt lgkmcnt(4)
	v_mfma_f32_16x16x32_bf16 v[0:3], v[168:171], v[172:175], v[0:3]
	s_waitcnt lgkmcnt(2)
	v_mfma_f32_16x16x32_bf16 v[0:3], v[176:179], v[180:183], v[0:3]
	s_waitcnt lgkmcnt(0)
	v_mfma_f32_16x16x32_bf16 v[0:3], v[184:187], v[188:191], v[0:3]
	s_waitcnt lgkmcnt(0)
	s_barrier
	s_waitcnt vmcnt(14)
	ds_write_b128 v149, v[124:127] offset:36864
	s_waitcnt vmcnt(13)
	ds_write_b128 v149, v[128:131] offset:45056
	s_waitcnt vmcnt(12)
	ds_write_b128 v149, v[132:135] offset:53248
	s_waitcnt vmcnt(11)
	ds_write_b128 v149, v[136:139] offset:61440
	s_waitcnt vmcnt(10)
	ds_write_b128 v150, v[140:143] offset:36864
	global_load_dwordx4 v[104:107], v144, s[98:99]
	global_load_dwordx4 v[108:111], v145, s[98:99]
	global_load_dwordx4 v[112:115], v146, s[98:99]
	global_load_dwordx4 v[116:119], v147, s[98:99]
	global_load_dwordx4 v[120:123], v148, s[96:97]
	s_add_u32 s98, s98, 0x100
	s_addc_u32 s99, s99, 0
	s_add_u32 s96, s96, 0x100
	s_addc_u32 s97, s97, 0
	ds_read_b128 v[160:163], v155
	ds_read_b128 v[164:167], v151
	ds_read_b128 v[168:171], v156
	ds_read_b128 v[172:175], v152
	ds_read_b128 v[176:179], v157
	ds_read_b128 v[180:183], v153
	ds_read_b128 v[184:187], v158
	ds_read_b128 v[188:191], v154
	s_waitcnt lgkmcnt(6)
	v_mfma_f32_16x16x32_bf16 v[0:3], v[160:163], v[164:167], v[0:3]
	s_waitcnt lgkmcnt(4)
	v_mfma_f32_16x16x32_bf16 v[0:3], v[168:171], v[172:175], v[0:3]
	s_waitcnt lgkmcnt(2)
	v_mfma_f32_16x16x32_bf16 v[0:3], v[176:179], v[180:183], v[0:3]
	s_waitcnt lgkmcnt(0)
	v_mfma_f32_16x16x32_bf16 v[0:3], v[184:187], v[188:191], v[0:3]
	s_waitcnt lgkmcnt(0)
	s_barrier
	s_waitcnt vmcnt(14)
	ds_write_b128 v149, v[64:67]
	s_waitcnt vmcnt(13)
	ds_write_b128 v149, v[68:71] offset:8192
	s_waitcnt vmcnt(12)
	ds_write_b128 v149, v[72:75] offset:16384
	s_waitcnt vmcnt(11)
	ds_write_b128 v149, v[76:79] offset:24576
	s_waitcnt vmcnt(10)
	ds_write_b128 v150, v[80:83]
	global_load_dwordx4 v[124:127], v144, s[98:99]
	global_load_dwordx4 v[128:131], v145, s[98:99]
	global_load_dwordx4 v[132:135], v146, s[98:99]
	global_load_dwordx4 v[136:139], v147, s[98:99]
	global_load_dwordx4 v[140:143], v148, s[96:97]
	s_add_u32 s98, s98, 0x100
	s_addc_u32 s99, s99, 0
	s_add_u32 s96, s96, 0x100
	s_addc_u32 s97, s97, 0
	ds_read_b128 v[160:163], v155 offset:36864
	ds_read_b128 v[164:167], v151 offset:36864
	ds_read_b128 v[168:171], v156 offset:36864
	ds_read_b128 v[172:175], v152 offset:36864
	ds_read_b128 v[176:179], v157 offset:36864
	ds_read_b128 v[180:183], v153 offset:36864
	ds_read_b128 v[184:187], v158 offset:36864
	ds_read_b128 v[188:191], v154 offset:36864
	s_waitcnt lgkmcnt(6)
	v_mfma_f32_16x16x32_bf16 v[0:3], v[160:163], v[164:167], v[0:3]
	s_waitcnt lgkmcnt(4)
	v_mfma_f32_16x16x32_bf16 v[0:3], v[168:171], v[172:175], v[0:3]
	s_waitcnt lgkmcnt(2)
	v_mfma_f32_16x16x32_bf16 v[0:3], v[176:179], v[180:183], v[0:3]
	s_waitcnt lgkmcnt(0)
	v_mfma_f32_16x16x32_bf16 v[0:3], v[184:187], v[188:191], v[0:3]
	s_waitcnt lgkmcnt(0)
	s_barrier
	s_waitcnt vmcnt(14)
	ds_write_b128 v149, v[84:87] offset:36864
	s_waitcnt vmcnt(13)
	ds_write_b128 v149, v[88:91] offset:45056
	s_waitcnt vmcnt(12)
	ds_write_b128 v149, v[92:95] offset:53248
	s_waitcnt vmcnt(11)
	ds_write_b128 v149, v[96:99] offset:61440
	s_waitcnt vmcnt(10)
	ds_write_b128 v150, v[100:103] offset:36864
	global_load_dwordx4 v[64:67], v144, s[98:99]
	global_load_dwordx4 v[68:71], v145, s[98:99]
	global_load_dwordx4 v[72:75], v146, s[98:99]
	global_load_dwordx4 v[76:79], v147, s[98:99]
	global_load_dwordx4 v[80:83], v148, s[96:97]
	s_add_u32 s98, s98, 0x100
	s_addc_u32 s99, s99, 0
	s_add_u32 s96, s96, 0x100
	s_addc_u32 s97, s97, 0
	ds_read_b128 v[160:163], v155
	ds_read_b128 v[164:167], v151
	ds_read_b128 v[168:171], v156
	ds_read_b128 v[172:175], v152
	ds_read_b128 v[176:179], v157
	ds_read_b128 v[180:183], v153
	ds_read_b128 v[184:187], v158
	ds_read_b128 v[188:191], v154
	s_waitcnt lgkmcnt(6)
	v_mfma_f32_16x16x32_bf16 v[0:3], v[160:163], v[164:167], v[0:3]
	s_waitcnt lgkmcnt(4)
	v_mfma_f32_16x16x32_bf16 v[0:3], v[168:171], v[172:175], v[0:3]
	s_waitcnt lgkmcnt(2)
	v_mfma_f32_16x16x32_bf16 v[0:3], v[176:179], v[180:183], v[0:3]
	s_waitcnt lgkmcnt(0)
	v_mfma_f32_16x16x32_bf16 v[0:3], v[184:187], v[188:191], v[0:3]
	s_waitcnt lgkmcnt(0)
	s_barrier
; template <int MODE>
; __device__ __forceinline__ void sgemm_sample(LAS unsigned char* lds, const bf16_t* A, const bf16_t* Bt, int K, const float* resid, float* out, bf16_t* xb, float* ssq_out, const float* ssq_in) {
;     ...
; #pragma unroll 8
;         for (int ks = 0; ks < K / 32; ++ks) {
;             const bf16x8 a = *(const bf16x8*)(ap + ks * 32); const bf16x8 b = *(const bf16x8*)(bp + ks * 32);
;             acc = __builtin_amdgcn_mfma_f32_16x16x32_bf16(b, a, acc, 0, 0, 0);
;         }
	s_waitcnt vmcnt(14)
	ds_write_b128 v149, v[104:107]
	s_waitcnt vmcnt(13)
	ds_write_b128 v149, v[108:111] offset:8192
	s_waitcnt vmcnt(12)
	ds_write_b128 v149, v[112:115] offset:16384
	s_waitcnt vmcnt(11)
	ds_write_b128 v149, v[116:119] offset:24576
	s_waitcnt vmcnt(10)
	ds_write_b128 v150, v[120:123]
	global_load_dwordx4 v[84:87], v144, s[98:99]
	global_load_dwordx4 v[88:91], v145, s[98:99]
	global_load_dwordx4 v[92:95], v146, s[98:99]
	global_load_dwordx4 v[96:99], v147, s[98:99]
	global_load_dwordx4 v[100:103], v148, s[96:97]
	s_add_u32 s98, s98, 0x100
	s_addc_u32 s99, s99, 0
	s_add_u32 s96, s96, 0x100
	s_addc_u32 s97, s97, 0
	ds_read_b128 v[160:163], v155 offset:36864
	ds_read_b128 v[164:167], v151 offset:36864
	ds_read_b128 v[168:171], v156 offset:36864
	ds_read_b128 v[172:175], v152 offset:36864
	ds_read_b128 v[176:179], v157 offset:36864
	ds_read_b128 v[180:183], v153 offset:36864
	ds_read_b128 v[184:187], v158 offset:36864
	ds_read_b128 v[188:191], v154 offset:36864
	s_waitcnt lgkmcnt(6)
	v_mfma_f32_16x16x32_bf16 v[0:3], v[160:163], v[164:167], v[0:3]
	s_waitcnt lgkmcnt(4)
	v_mfma_f32_16x16x32_bf16 v[0:3], v[168:171], v[172:175], v[0:3]
	s_waitcnt lgkmcnt(2)
	v_mfma_f32_16x16x32_bf16 v[0:3], v[176:179], v[180:183], v[0:3]
	s_waitcnt lgkmcnt(0)
	v_mfma_f32_16x16x32_bf16 v[0:3], v[184:187], v[188:191], v[0:3]
	s_waitcnt lgkmcnt(0)
	s_barrier
	s_waitcnt vmcnt(14)
	ds_write_b128 v149, v[124:127] offset:36864
	s_waitcnt vmcnt(13)
	ds_write_b128 v149, v[128:131] offset:45056
	s_waitcnt vmcnt(12)
	ds_write_b128 v149, v[132:135] offset:53248
	s_waitcnt vmcnt(11)
	ds_write_b128 v149, v[136:139] offset:61440
	s_waitcnt vmcnt(10)
	ds_write_b128 v150, v[140:143] offset:36864
	global_load_dwordx4 v[104:107], v144, s[98:99]
	global_load_dwordx4 v[108:111], v145, s[98:99]
	global_load_dwordx4 v[112:115], v146, s[98:99]
	global_load_dwordx4 v[116:119], v147, s[98:99]
	global_load_dwordx4 v[120:123], v148, s[96:97]
	s_add_u32 s98, s98, 0x100
	s_addc_u32 s99, s99, 0
	s_add_u32 s96, s96, 0x100
	s_addc_u32 s97, s97, 0
	ds_read_b128 v[160:163], v155
	ds_read_b128 v[164:167], v151
	ds_read_b128 v[168:171], v156
	ds_read_b128 v[172:175], v152
	ds_read_b128 v[176:179], v157
	ds_read_b128 v[180:183], v153
	ds_read_b128 v[184:187], v158
	ds_read_b128 v[188:191], v154
	s_waitcnt lgkmcnt(6)
	v_mfma_f32_16x16x32_bf16 v[0:3], v[160:163], v[164:167], v[0:3]
	s_waitcnt lgkmcnt(4)
	v_mfma_f32_16x16x32_bf16 v[0:3], v[168:171], v[172:175], v[0:3]
	s_waitcnt lgkmcnt(2)
	v_mfma_f32_16x16x32_bf16 v[0:3], v[176:179], v[180:183], v[0:3]
	s_waitcnt lgkmcnt(0)
	v_mfma_f32_16x16x32_bf16 v[0:3], v[184:187], v[188:191], v[0:3]
	s_waitcnt lgkmcnt(0)
	s_barrier
	s_waitcnt vmcnt(14)
	ds_write_b128 v149, v[64:67]
	s_waitcnt vmcnt(13)
	ds_write_b128 v149, v[68:71] offset:8192
	s_waitcnt vmcnt(12)
	ds_write_b128 v149, v[72:75] offset:16384
	s_waitcnt vmcnt(11)
	ds_write_b128 v149, v[76:79] offset:24576
	s_waitcnt vmcnt(10)
	ds_write_b128 v150, v[80:83]
	global_load_dwordx4 v[124:127], v144, s[98:99]
	global_load_dwordx4 v[128:131], v145, s[98:99]
	global_load_dwordx4 v[132:135], v146, s[98:99]
	global_load_dwordx4 v[136:139], v147, s[98:99]
	global_load_dwordx4 v[140:143], v148, s[96:97]
	s_add_u32 s98, s98, 0x100
	s_addc_u32 s99, s99, 0
	s_add_u32 s96, s96, 0x100
	s_addc_u32 s97, s97, 0
	ds_read_b128 v[160:163], v155 offset:36864
	ds_read_b128 v[164:167], v151 offset:36864
	ds_read_b128 v[168:171], v156 offset:36864
	ds_read_b128 v[172:175], v152 offset:36864
	ds_read_b128 v[176:179], v157 offset:36864
	ds_read_b128 v[180:183], v153 offset:36864
	ds_read_b128 v[184:187], v158 offset:36864
	ds_read_b128 v[188:191], v154 offset:36864
	s_waitcnt lgkmcnt(6)
	v_mfma_f32_16x16x32_bf16 v[0:3], v[160:163], v[164:167], v[0:3]
	s_waitcnt lgkmcnt(4)
	v_mfma_f32_16x16x32_bf16 v[0:3], v[168:171], v[172:175], v[0:3]
	s_waitcnt lgkmcnt(2)
	v_mfma_f32_16x16x32_bf16 v[0:3], v[176:179], v[180:183], v[0:3]
	s_waitcnt lgkmcnt(0)
	v_mfma_f32_16x16x32_bf16 v[0:3], v[184:187], v[188:191], v[0:3]
	s_waitcnt lgkmcnt(0)
	s_barrier
	s_waitcnt vmcnt(14)
	ds_write_b128 v149, v[84:87] offset:36864
	s_waitcnt vmcnt(13)
	ds_write_b128 v149, v[88:91] offset:45056
	s_waitcnt vmcnt(12)
	ds_write_b128 v149, v[92:95] offset:53248
	s_waitcnt vmcnt(11)
	ds_write_b128 v149, v[96:99] offset:61440
	s_waitcnt vmcnt(10)
	ds_write_b128 v150, v[100:103] offset:36864
	global_load_dwordx4 v[64:67], v144, s[98:99]
	global_load_dwordx4 v[68:71], v145, s[98:99]
	global_load_dwordx4 v[72:75], v146, s[98:99]
	global_load_dwordx4 v[76:79], v147, s[98:99]
	global_load_dwordx4 v[80:83], v148, s[96:97]
	s_add_u32 s98, s98, 0x100
	s_addc_u32 s99, s99, 0
	s_add_u32 s96, s96, 0x100
	s_addc_u32 s97, s97, 0
	ds_read_b128 v[160:163], v155
	ds_read_b128 v[164:167], v151
	ds_read_b128 v[168:171], v156
	ds_read_b128 v[172:175], v152
	ds_read_b128 v[176:179], v157
	ds_read_b128 v[180:183], v153
	ds_read_b128 v[184:187], v158
	ds_read_b128 v[188:191], v154
	s_waitcnt lgkmcnt(6)
	v_mfma_f32_16x16x32_bf16 v[0:3], v[160:163], v[164:167], v[0:3]
	s_waitcnt lgkmcnt(4)
	v_mfma_f32_16x16x32_bf16 v[0:3], v[168:171], v[172:175], v[0:3]
	s_waitcnt lgkmcnt(2)
	v_mfma_f32_16x16x32_bf16 v[0:3], v[176:179], v[180:183], v[0:3]
	s_waitcnt lgkmcnt(0)
	v_mfma_f32_16x16x32_bf16 v[0:3], v[184:187], v[188:191], v[0:3]
	s_waitcnt lgkmcnt(0)
	s_barrier
; template <int MODE>
; __device__ __forceinline__ void sgemm_sample(LAS unsigned char* lds, const bf16_t* A, const bf16_t* Bt, int K, const float* resid, float* out, bf16_t* xb, float* ssq_out, const float* ssq_in) {
;     ...
; #pragma unroll 8
;         for (int ks = 0; ks < K / 32; ++ks) {
;             const bf16x8 a = *(const bf16x8*)(ap + ks * 32); const bf16x8 b = *(const bf16x8*)(bp + ks * 32);
;             acc = __builtin_amdgcn_mfma_f32_16x16x32_bf16(b, a, acc, 0, 0, 0);
;         }
	s_waitcnt vmcnt(14)
	ds_write_b128 v149, v[104:107]
	s_waitcnt vmcnt(13)
	ds_write_b128 v149, v[108:111] offset:8192
	s_waitcnt vmcnt(12)
	ds_write_b128 v149, v[112:115] offset:16384
	s_waitcnt vmcnt(11)
	ds_write_b128 v149, v[116:119] offset:24576
	s_waitcnt vmcnt(10)
	ds_write_b128 v150, v[120:123]
	global_load_dwordx4 v[84:87], v144, s[98:99]
	global_load_dwordx4 v[88:91], v145, s[98:99]
	global_load_dwordx4 v[92:95], v146, s[98:99]
	global_load_dwordx4 v[96:99], v147, s[98:99]
	global_load_dwordx4 v[100:103], v148, s[96:97]
	s_add_u32 s98, s98, 0x100
	s_addc_u32 s99, s99, 0
	s_add_u32 s96, s96, 0x100
	s_addc_u32 s97, s97, 0
	ds_read_b128 v[160:163], v155 offset:36864
	ds_read_b128 v[164:167], v151 offset:36864
	ds_read_b128 v[168:171], v156 offset:36864
	ds_read_b128 v[172:175], v152 offset:36864
	ds_read_b128 v[176:179], v157 offset:36864
	ds_read_b128 v[180:183], v153 offset:36864
	ds_read_b128 v[184:187], v158 offset:36864
	ds_read_b128 v[188:191], v154 offset:36864
	s_waitcnt lgkmcnt(6)
	v_mfma_f32_16x16x32_bf16 v[0:3], v[160:163], v[164:167], v[0:3]
	s_waitcnt lgkmcnt(4)
	v_mfma_f32_16x16x32_bf16 v[0:3], v[168:171], v[172:175], v[0:3]
	s_waitcnt lgkmcnt(2)
	v_mfma_f32_16x16x32_bf16 v[0:3], v[176:179], v[180:183], v[0:3]
	s_waitcnt lgkmcnt(0)
	v_mfma_f32_16x16x32_bf16 v[0:3], v[184:187], v[188:191], v[0:3]
	s_waitcnt lgkmcnt(0)
	s_barrier
	s_waitcnt vmcnt(14)
	ds_write_b128 v149, v[124:127] offset:36864
	s_waitcnt vmcnt(13)
	ds_write_b128 v149, v[128:131] offset:45056
	s_waitcnt vmcnt(12)
	ds_write_b128 v149, v[132:135] offset:53248
	s_waitcnt vmcnt(11)
	ds_write_b128 v149, v[136:139] offset:61440
	s_waitcnt vmcnt(10)
	ds_write_b128 v150, v[140:143] offset:36864
	global_load_dwordx4 v[104:107], v144, s[98:99]
	global_load_dwordx4 v[108:111], v145, s[98:99]
	global_load_dwordx4 v[112:115], v146, s[98:99]
	global_load_dwordx4 v[116:119], v147, s[98:99]
	global_load_dwordx4 v[120:123], v148, s[96:97]
	s_add_u32 s98, s98, 0x100
	s_addc_u32 s99, s99, 0
	s_add_u32 s96, s96, 0x100
	s_addc_u32 s97, s97, 0
	ds_read_b128 v[160:163], v155
	ds_read_b128 v[164:167], v151
	ds_read_b128 v[168:171], v156
	ds_read_b128 v[172:175], v152
	ds_read_b128 v[176:179], v157
	ds_read_b128 v[180:183], v153
	ds_read_b128 v[184:187], v158
	ds_read_b128 v[188:191], v154
	s_waitcnt lgkmcnt(6)
	v_mfma_f32_16x16x32_bf16 v[0:3], v[160:163], v[164:167], v[0:3]
	s_waitcnt lgkmcnt(4)
	v_mfma_f32_16x16x32_bf16 v[0:3], v[168:171], v[172:175], v[0:3]
	s_waitcnt lgkmcnt(2)
	v_mfma_f32_16x16x32_bf16 v[0:3], v[176:179], v[180:183], v[0:3]
	s_waitcnt lgkmcnt(0)
	v_mfma_f32_16x16x32_bf16 v[0:3], v[184:187], v[188:191], v[0:3]
	s_waitcnt lgkmcnt(0)
	s_barrier
	s_waitcnt vmcnt(14)
	ds_write_b128 v149, v[64:67]
	s_waitcnt vmcnt(13)
	ds_write_b128 v149, v[68:71] offset:8192
	s_waitcnt vmcnt(12)
	ds_write_b128 v149, v[72:75] offset:16384
	s_waitcnt vmcnt(11)
	ds_write_b128 v149, v[76:79] offset:24576
	s_waitcnt vmcnt(10)
	ds_write_b128 v150, v[80:83]
	global_load_dwordx4 v[124:127], v144, s[98:99]
	global_load_dwordx4 v[128:131], v145, s[98:99]
	global_load_dwordx4 v[132:135], v146, s[98:99]
	global_load_dwordx4 v[136:139], v147, s[98:99]
	global_load_dwordx4 v[140:143], v148, s[96:97]
	s_add_u32 s98, s98, 0x100
	s_addc_u32 s99, s99, 0
	s_add_u32 s96, s96, 0x100
	s_addc_u32 s97, s97, 0
	ds_read_b128 v[160:163], v155 offset:36864
	ds_read_b128 v[164:167], v151 offset:36864
	ds_read_b128 v[168:171], v156 offset:36864
	ds_read_b128 v[172:175], v152 offset:36864
	ds_read_b128 v[176:179], v157 offset:36864
	ds_read_b128 v[180:183], v153 offset:36864
	ds_read_b128 v[184:187], v158 offset:36864
	ds_read_b128 v[188:191], v154 offset:36864
	s_waitcnt lgkmcnt(6)
	v_mfma_f32_16x16x32_bf16 v[0:3], v[160:163], v[164:167], v[0:3]
	s_waitcnt lgkmcnt(4)
	v_mfma_f32_16x16x32_bf16 v[0:3], v[168:171], v[172:175], v[0:3]
	s_waitcnt lgkmcnt(2)
	v_mfma_f32_16x16x32_bf16 v[0:3], v[176:179], v[180:183], v[0:3]
	s_waitcnt lgkmcnt(0)
	v_mfma_f32_16x16x32_bf16 v[0:3], v[184:187], v[188:191], v[0:3]
	s_waitcnt lgkmcnt(0)
	s_barrier
	s_waitcnt vmcnt(14)
	ds_write_b128 v149, v[84:87] offset:36864
	s_waitcnt vmcnt(13)
	ds_write_b128 v149, v[88:91] offset:45056
	s_waitcnt vmcnt(12)
	ds_write_b128 v149, v[92:95] offset:53248
	s_waitcnt vmcnt(11)
	ds_write_b128 v149, v[96:99] offset:61440
	s_waitcnt vmcnt(10)
	ds_write_b128 v150, v[100:103] offset:36864
	global_load_dwordx4 v[64:67], v144, s[98:99]
	global_load_dwordx4 v[68:71], v145, s[98:99]
	global_load_dwordx4 v[72:75], v146, s[98:99]
	global_load_dwordx4 v[76:79], v147, s[98:99]
	global_load_dwordx4 v[80:83], v148, s[96:97]
	s_add_u32 s98, s98, 0x100
	s_addc_u32 s99, s99, 0
	s_add_u32 s96, s96, 0x100
	s_addc_u32 s97, s97, 0
	ds_read_b128 v[160:163], v155
	ds_read_b128 v[164:167], v151
	ds_read_b128 v[168:171], v156
	ds_read_b128 v[172:175], v152
	ds_read_b128 v[176:179], v157
	ds_read_b128 v[180:183], v153
	ds_read_b128 v[184:187], v158
	ds_read_b128 v[188:191], v154
	s_waitcnt lgkmcnt(6)
	v_mfma_f32_16x16x32_bf16 v[0:3], v[160:163], v[164:167], v[0:3]
	s_waitcnt lgkmcnt(4)
	v_mfma_f32_16x16x32_bf16 v[0:3], v[168:171], v[172:175], v[0:3]
	s_waitcnt lgkmcnt(2)
	v_mfma_f32_16x16x32_bf16 v[0:3], v[176:179], v[180:183], v[0:3]
	s_waitcnt lgkmcnt(0)
	v_mfma_f32_16x16x32_bf16 v[0:3], v[184:187], v[188:191], v[0:3]
	s_waitcnt lgkmcnt(0)
	s_barrier
; template <int MODE>
; __device__ __forceinline__ void sgemm_sample(LAS unsigned char* lds, const bf16_t* A, const bf16_t* Bt, int K, const float* resid, float* out, bf16_t* xb, float* ssq_out, const float* ssq_in) {
;     ...
; #pragma unroll 8
;         for (int ks = 0; ks < K / 32; ++ks) {
;             const bf16x8 a = *(const bf16x8*)(ap + ks * 32); const bf16x8 b = *(const bf16x8*)(bp + ks * 32);
;             acc = __builtin_amdgcn_mfma_f32_16x16x32_bf16(b, a, acc, 0, 0, 0);
;         }
	s_waitcnt vmcnt(14)
	ds_write_b128 v149, v[104:107]
	s_waitcnt vmcnt(13)
	ds_write_b128 v149, v[108:111] offset:8192
	s_waitcnt vmcnt(12)
	ds_write_b128 v149, v[112:115] offset:16384
	s_waitcnt vmcnt(11)
	ds_write_b128 v149, v[116:119] offset:24576
	s_waitcnt vmcnt(10)
	ds_write_b128 v150, v[120:123]
	global_load_dwordx4 v[84:87], v144, s[98:99]
	global_load_dwordx4 v[88:91], v145, s[98:99]
	global_load_dwordx4 v[92:95], v146, s[98:99]
	global_load_dwordx4 v[96:99], v147, s[98:99]
	global_load_dwordx4 v[100:103], v148, s[96:97]
	s_add_u32 s98, s98, 0x100
	s_addc_u32 s99, s99, 0
	s_add_u32 s96, s96, 0x100
	s_addc_u32 s97, s97, 0
	ds_read_b128 v[160:163], v155 offset:36864
	ds_read_b128 v[164:167], v151 offset:36864
	ds_read_b128 v[168:171], v156 offset:36864
	ds_read_b128 v[172:175], v152 offset:36864
	ds_read_b128 v[176:179], v157 offset:36864
	ds_read_b128 v[180:183], v153 offset:36864
	ds_read_b128 v[184:187], v158 offset:36864
	ds_read_b128 v[188:191], v154 offset:36864
	s_waitcnt lgkmcnt(6)
	v_mfma_f32_16x16x32_bf16 v[0:3], v[160:163], v[164:167], v[0:3]
	s_waitcnt lgkmcnt(4)
	v_mfma_f32_16x16x32_bf16 v[0:3], v[168:171], v[172:175], v[0:3]
	s_waitcnt lgkmcnt(2)
	v_mfma_f32_16x16x32_bf16 v[0:3], v[176:179], v[180:183], v[0:3]
	s_waitcnt lgkmcnt(0)
	v_mfma_f32_16x16x32_bf16 v[0:3], v[184:187], v[188:191], v[0:3]
	s_waitcnt lgkmcnt(0)
	s_barrier
	s_waitcnt vmcnt(14)
	ds_write_b128 v149, v[124:127] offset:36864
	s_waitcnt vmcnt(13)
	ds_write_b128 v149, v[128:131] offset:45056
	s_waitcnt vmcnt(12)
	ds_write_b128 v149, v[132:135] offset:53248
	s_waitcnt vmcnt(11)
	ds_write_b128 v149, v[136:139] offset:61440
	s_waitcnt vmcnt(10)
	ds_write_b128 v150, v[140:143] offset:36864
	ds_read_b128 v[160:163], v155
	ds_read_b128 v[164:167], v151
	ds_read_b128 v[168:171], v156
	ds_read_b128 v[172:175], v152
	ds_read_b128 v[176:179], v157
	ds_read_b128 v[180:183], v153
	ds_read_b128 v[184:187], v158
	ds_read_b128 v[188:191], v154
	s_waitcnt lgkmcnt(6)
	v_mfma_f32_16x16x32_bf16 v[0:3], v[160:163], v[164:167], v[0:3]
	s_waitcnt lgkmcnt(4)
	v_mfma_f32_16x16x32_bf16 v[0:3], v[168:171], v[172:175], v[0:3]
	s_waitcnt lgkmcnt(2)
	v_mfma_f32_16x16x32_bf16 v[0:3], v[176:179], v[180:183], v[0:3]
	s_waitcnt lgkmcnt(0)
	v_mfma_f32_16x16x32_bf16 v[0:3], v[184:187], v[188:191], v[0:3]
	s_waitcnt lgkmcnt(0)
	s_barrier
	s_waitcnt vmcnt(9)
	ds_write_b128 v149, v[64:67]
	s_waitcnt vmcnt(8)
	ds_write_b128 v149, v[68:71] offset:8192
	s_waitcnt vmcnt(7)
	ds_write_b128 v149, v[72:75] offset:16384
	s_waitcnt vmcnt(6)
	ds_write_b128 v149, v[76:79] offset:24576
	s_waitcnt vmcnt(5)
	ds_write_b128 v150, v[80:83]
	ds_read_b128 v[160:163], v155 offset:36864
	ds_read_b128 v[164:167], v151 offset:36864
	ds_read_b128 v[168:171], v156 offset:36864
	ds_read_b128 v[172:175], v152 offset:36864
	ds_read_b128 v[176:179], v157 offset:36864
	ds_read_b128 v[180:183], v153 offset:36864
	ds_read_b128 v[184:187], v158 offset:36864
	ds_read_b128 v[188:191], v154 offset:36864
	s_waitcnt lgkmcnt(6)
	v_mfma_f32_16x16x32_bf16 v[0:3], v[160:163], v[164:167], v[0:3]
	s_waitcnt lgkmcnt(4)
	v_mfma_f32_16x16x32_bf16 v[0:3], v[168:171], v[172:175], v[0:3]
	s_waitcnt lgkmcnt(2)
	v_mfma_f32_16x16x32_bf16 v[0:3], v[176:179], v[180:183], v[0:3]
	s_waitcnt lgkmcnt(0)
	v_mfma_f32_16x16x32_bf16 v[0:3], v[184:187], v[188:191], v[0:3]
	s_waitcnt lgkmcnt(0)
	s_barrier
	s_waitcnt vmcnt(4)
	ds_write_b128 v149, v[84:87] offset:36864
	s_waitcnt vmcnt(3)
	ds_write_b128 v149, v[88:91] offset:45056
	s_waitcnt vmcnt(2)
	ds_write_b128 v149, v[92:95] offset:53248
	s_waitcnt vmcnt(1)
	ds_write_b128 v149, v[96:99] offset:61440
	s_waitcnt vmcnt(0)
	ds_write_b128 v150, v[100:103] offset:36864
	ds_read_b128 v[160:163], v155
	ds_read_b128 v[164:167], v151
	ds_read_b128 v[168:171], v156
	ds_read_b128 v[172:175], v152
	ds_read_b128 v[176:179], v157
	ds_read_b128 v[180:183], v153
	ds_read_b128 v[184:187], v158
	ds_read_b128 v[188:191], v154
	s_waitcnt lgkmcnt(6)
	v_mfma_f32_16x16x32_bf16 v[0:3], v[160:163], v[164:167], v[0:3]
	s_waitcnt lgkmcnt(4)
	v_mfma_f32_16x16x32_bf16 v[0:3], v[168:171], v[172:175], v[0:3]
	s_waitcnt lgkmcnt(2)
	v_mfma_f32_16x16x32_bf16 v[0:3], v[176:179], v[180:183], v[0:3]
	s_waitcnt lgkmcnt(0)
	v_mfma_f32_16x16x32_bf16 v[0:3], v[184:187], v[188:191], v[0:3]
	s_waitcnt lgkmcnt(0)
	s_barrier
	ds_read_b128 v[160:163], v155 offset:36864
	ds_read_b128 v[164:167], v151 offset:36864
	ds_read_b128 v[168:171], v156 offset:36864
	ds_read_b128 v[172:175], v152 offset:36864
	ds_read_b128 v[176:179], v157 offset:36864
	ds_read_b128 v[180:183], v153 offset:36864
	ds_read_b128 v[184:187], v158 offset:36864
	ds_read_b128 v[188:191], v154 offset:36864
	s_waitcnt lgkmcnt(6)
	v_mfma_f32_16x16x32_bf16 v[0:3], v[160:163], v[164:167], v[0:3]
	s_waitcnt lgkmcnt(4)
	v_mfma_f32_16x16x32_bf16 v[0:3], v[168:171], v[172:175], v[0:3]
	s_waitcnt lgkmcnt(2)
	v_mfma_f32_16x16x32_bf16 v[0:3], v[176:179], v[180:183], v[0:3]
	s_waitcnt lgkmcnt(0)
	v_mfma_f32_16x16x32_bf16 v[0:3], v[184:187], v[188:191], v[0:3]
	s_nop 7
	s_branch .Lsgx3_done
; template <int MODE>
; __device__ __forceinline__ void sgemm_sample(LAS unsigned char* lds, const bf16_t* A, const bf16_t* Bt, int K, const float* resid, float* out, bf16_t* xb, float* ssq_out, const float* ssq_in) {
;     ...
;         const bf16_t* ap = A + (size_t)row * K + fq * 8; const bf16_t* bp = Bt + (size_t)(ct * 16 + fr) * K + fq * 8;
;         f32x4 acc = {0.f, 0.f, 0.f, 0.f};
; #pragma unroll 8
;         for (int ks = 0; ks < K / 32; ++ks) {
;             const bf16x8 a = *(const bf16x8*)(ap + ks * 32); const bf16x8 b = *(const bf16x8*)(bp + ks * 32);
;             acc = __builtin_amdgcn_mfma_f32_16x16x32_bf16(b, a, acc, 0, 0, 0);
;         }
;         if (MODE == 0) {
;             const f32x4 x = *(const f32x4*)(resid + (size_t)(row - NTOKP) * D + col0) + acc;
;             *(f32x4*)(out + (size_t)row * D + col0) = x;
.LBB0_1349:
	v_lshl_add_u64 v[18:19], v[10:11], 0, s[0:1]
	v_add_co_u32_e32 v54, vcc, 0x22c0000, v18
	v_lshl_add_u64 v[20:21], v[12:13], 0, s[0:1]
	s_nop 0
	v_addc_co_u32_e32 v55, vcc, 0, v19, vcc
	v_add_co_u32_e32 v56, vcc, 0x1d40000, v20
	s_add_u32 s0, s0, 0x200
	s_nop 0
	v_addc_co_u32_e32 v57, vcc, 0, v21, vcc
	global_load_dwordx4 v[18:21], v[54:55], off
	global_load_dwordx4 v[22:25], v[54:55], off offset:64
	global_load_dwordx4 v[26:29], v[54:55], off offset:128
	global_load_dwordx4 v[30:33], v[54:55], off offset:192
	global_load_dwordx4 v[34:37], v[54:55], off offset:256
	global_load_dwordx4 v[38:41], v[56:57], off
	global_load_dwordx4 v[42:45], v[56:57], off offset:64
	global_load_dwordx4 v[46:49], v[56:57], off offset:128
	global_load_dwordx4 v[50:53], v[56:57], off offset:192
	s_addc_u32 s1, s1, 0
	s_cmpk_eq_i32 s0, 0x1600
	s_waitcnt vmcnt(3)
	v_mfma_f32_16x16x32_bf16 v[0:3], v[38:41], v[18:21], v[0:3]
	global_load_dwordx4 v[18:21], v[56:57], off offset:256
	s_waitcnt vmcnt(3)
	v_mfma_f32_16x16x32_bf16 v[0:3], v[42:45], v[22:25], v[0:3]
	global_load_dwordx4 v[22:25], v[56:57], off offset:320
	s_waitcnt vmcnt(3)
	v_mfma_f32_16x16x32_bf16 v[0:3], v[46:49], v[26:29], v[0:3]
	global_load_dwordx4 v[26:29], v[54:55], off offset:320
	s_waitcnt vmcnt(3)
	v_mfma_f32_16x16x32_bf16 v[0:3], v[50:53], v[30:33], v[0:3]
	global_load_dwordx4 v[30:33], v[56:57], off offset:384
	global_load_dwordx4 v[38:41], v[54:55], off offset:384
	s_waitcnt vmcnt(4)
	v_mfma_f32_16x16x32_bf16 v[0:3], v[18:21], v[34:37], v[0:3]
	global_load_dwordx4 v[18:21], v[56:57], off offset:448
	s_waitcnt vmcnt(3)
	v_mfma_f32_16x16x32_bf16 v[0:3], v[22:25], v[26:29], v[0:3]
	global_load_dwordx4 v[22:25], v[54:55], off offset:448
	s_waitcnt vmcnt(2)
	v_mfma_f32_16x16x32_bf16 v[0:3], v[30:33], v[38:41], v[0:3]
	s_waitcnt vmcnt(0)
	v_mfma_f32_16x16x32_bf16 v[0:3], v[18:21], v[22:25], v[0:3]
	s_cbranch_scc0 .LBB0_1349
	v_or_b32_e32 v4, s10, v15
	v_lshlrev_b64 v[12:13], 12, v[8:9]
	v_lshl_add_u64 v[8:9], s[8:9], 0, v[12:13]
	v_lshlrev_b32_e32 v4, 2, v4
	v_lshl_add_u64 v[8:9], v[8:9], 0, v[4:5]
	v_add_co_u32_e32 v8, vcc, 0xf8000000, v8
	s_add_i32 s3, s3, s4
	s_nop 0
	v_addc_co_u32_e32 v9, vcc, -1, v9, vcc
	global_load_dwordx4 v[8:11], v[8:9], off
.Lsgx3_done:
	v_lshl_add_u64 v[12:13], s[90:91], 0, v[12:13]
	v_lshl_add_u64 v[12:13], v[12:13], 0, v[4:5]
	s_cmpk_gt_i32 s3, 0x7ff
	s_waitcnt vmcnt(0)
	v_pk_add_f32 v[2:3], v[2:3], v[10:11]
	v_pk_add_f32 v[0:1], v[0:1], v[8:9]
	global_store_dwordx4 v[12:13], v[0:3], off
	s_cbranch_scc0 .LBB0_1348
